# cross-attention softmax with one packed fma per score pair and packed sums as well
# baseline (speedup 1.0000x reference)
; #define LAS __attribute__((address_space(3)))
; #define MFMA16(a, b, c) __builtin_amdgcn_mfma_f32_16x16x32_bf16((a), (b), (c), 0, 0, 0)
; #define DSEC(k) do { if (PROBE_DSEC) { const unsigned long long tn_ = __builtin_amdgcn_s_memrealtime(); if (PROBE_DSEC == (k)) tsec += tn_ - tl_; tl_ = tn_; } } while (0)
; #define XK_LOAD(R, b_, h_, hh_) do { _Pragma("unroll") for (int i = 0; i < 8; ++i) { const int p = tid + 512 * i, m = p >> 4, cb = p & 15; R[i] = *(const u32x4*)(memK + (size_t)((b_) * NMEM + m) * D + (h_) * 256 + 128 * (hh_) + 8 * cb); } } while (0)
; #define XK_WRITE(R) do { _Pragma("unroll") for (int i = 0; i < 8; ++i) { const int p = tid + 512 * i, m = p >> 4, cb = p & 15; *(LAS u32x4*)(KL + m * KSTR + 16 * cb) = R[i]; } } while (0)
; #define XV_LOAD(R, b_, h_, hh_) do { _Pragma("unroll") for (int i = 0; i < 8; ++i) { const int p = tid + 512 * i, dhr = p >> 5, c = p & 31; R[i] = *(const u32x4*)(memVT + (size_t)((h_) * 256 + 128 * (hh_) + dhr) * MROWS + (b_) * NMEM + 8 * c); } } while (0)
; #define XV_WRITE(R) do { _Pragma("unroll") for (int i = 0; i < 8; ++i) { const int p = tid + 512 * i, dhr = p >> 5, c = p & 31; u32x2 lo, hi; lo.x = R[i].x; lo.y = R[i].y; hi.x = R[i].z; hi.y = R[i].w; \
;         *(LAS u32x2*)(VL + vt_off(dhr, 2 * c)) = lo; *(LAS u32x2*)(VL + vt_off(dhr, 2 * c + 1)) = hi; } } while (0)
; DI void xattn_phase(LAS unsigned char* L, const bf16* Qx, const bf16* memK, const bf16* memVT, bf16* Ox, int G, int bid, int tid, unsigned long long& tsec) {
;     ...
;         for (int hh = 0; hh < 2; ++hh) {
;             __syncthreads();
;             XK_WRITE(ra);
;             if (hh == 0) { XV_WRITE(rb); XK_LOAD(ra, b, h, 1); XV_LOAD(rb, b, h, 1); }
;             else XK_LOAD(ra, bn, hn, 0);
;             __syncthreads();
;             DSEC(11);
; #pragma unroll
;             for (int k4 = 0; k4 < 4; ++k4) { const bf16x8 qk = *(const bf16x8*)(Qx + tq * D + h * 256 + 128 * hh + 32 * k4 + 8 * fq);
; #pragma unroll
;                 for (int k8 = 0; k8 < 4; ++k8) { bf16x8 av[4];
; #pragma unroll
;                     for (int kt = 0; kt < 4; ++kt) av[kt] = *(const LAS bf16x8*)(KL + (16 * (4 * k8 + kt) + fr) * KSTR + (32 * k4 + 8 * fq) * 2);
; #pragma unroll
;                     for (int kt = 0; kt < 4; ++kt) s[4 * k8 + kt] = MFMA16(av[kt], qk, s[4 * k8 + kt]); } }
.Lxa_loop:
	s_add_u32 s44, s24, 256
	s_addc_u32 s45, s25, 0
	s_add_u32 s46, s44, 0x8000
	s_addc_u32 s47, s45, 0
	s_add_u32 m0, s49, 65536
	s_nop 0
	global_load_lds_dwordx4 v198, s[44:45]
	s_add_u32 m0, s49, 66560
	s_nop 0
	global_load_lds_dwordx4 v199, s[44:45]
	s_add_u32 m0, s49, 67584
	s_nop 0
	global_load_lds_dwordx4 v200, s[44:45]
	s_add_u32 m0, s49, 68608
	s_nop 0
	global_load_lds_dwordx4 v201, s[44:45]
	s_add_u32 m0, s49, 69632
	s_nop 0
	global_load_lds_dwordx4 v198, s[46:47]
	s_add_u32 m0, s49, 70656
	s_nop 0
	global_load_lds_dwordx4 v199, s[46:47]
	s_add_u32 m0, s49, 71680
	s_nop 0
	global_load_lds_dwordx4 v200, s[46:47]
	s_add_u32 m0, s49, 72704
	s_nop 0
	global_load_lds_dwordx4 v201, s[46:47]
	ds_read_b128 v[98:101], v206 offset:0
	ds_read_b128 v[102:105], v206 offset:4096
	ds_read_b128 v[106:109], v206 offset:8192
	ds_read_b128 v[110:113], v206 offset:12288
	ds_read_b128 v[114:117], v206 offset:16384
	ds_read_b128 v[118:121], v206 offset:20480
	ds_read_b128 v[122:125], v206 offset:24576
	ds_read_b128 v[126:129], v206 offset:28672
	ds_read_b128 v[130:133], v206 offset:32768
	ds_read_b128 v[134:137], v206 offset:36864
	ds_read_b128 v[138:141], v206 offset:40960
	ds_read_b128 v[142:145], v206 offset:45056
	ds_read_b128 v[146:149], v206 offset:49152
	ds_read_b128 v[150:153], v206 offset:53248
	ds_read_b128 v[154:157], v206 offset:57344
	ds_read_b128 v[158:161], v206 offset:61440
	s_waitcnt lgkmcnt(8)
	v_mfma_f32_16x16x32_bf16 v[2:5], v[98:101], v[66:69], 0
	ds_read_b128 v[98:101], v207 offset:0
	v_mfma_f32_16x16x32_bf16 v[6:9], v[102:105], v[66:69], 0
	ds_read_b128 v[102:105], v207 offset:4096
	v_mfma_f32_16x16x32_bf16 v[10:13], v[106:109], v[66:69], 0
	ds_read_b128 v[106:109], v207 offset:8192
	v_mfma_f32_16x16x32_bf16 v[14:17], v[110:113], v[66:69], 0
	ds_read_b128 v[110:113], v207 offset:12288
	v_mfma_f32_16x16x32_bf16 v[18:21], v[114:117], v[66:69], 0
	ds_read_b128 v[114:117], v207 offset:16384
	v_mfma_f32_16x16x32_bf16 v[22:25], v[118:121], v[66:69], 0
	ds_read_b128 v[118:121], v207 offset:20480
	v_mfma_f32_16x16x32_bf16 v[26:29], v[122:125], v[66:69], 0
	ds_read_b128 v[122:125], v207 offset:24576
	v_mfma_f32_16x16x32_bf16 v[30:33], v[126:129], v[66:69], 0
	ds_read_b128 v[126:129], v207 offset:28672
	s_waitcnt lgkmcnt(8)
	v_mfma_f32_16x16x32_bf16 v[34:37], v[130:133], v[66:69], 0
	ds_read_b128 v[130:133], v207 offset:32768
	v_mfma_f32_16x16x32_bf16 v[38:41], v[134:137], v[66:69], 0
	ds_read_b128 v[134:137], v207 offset:36864
	v_mfma_f32_16x16x32_bf16 v[42:45], v[138:141], v[66:69], 0
	ds_read_b128 v[138:141], v207 offset:40960
	v_mfma_f32_16x16x32_bf16 v[46:49], v[142:145], v[66:69], 0
	ds_read_b128 v[142:145], v207 offset:45056
	v_mfma_f32_16x16x32_bf16 v[50:53], v[146:149], v[66:69], 0
	ds_read_b128 v[146:149], v207 offset:49152
	v_mfma_f32_16x16x32_bf16 v[54:57], v[150:153], v[66:69], 0
	ds_read_b128 v[150:153], v207 offset:53248
	v_mfma_f32_16x16x32_bf16 v[58:61], v[154:157], v[66:69], 0
	ds_read_b128 v[154:157], v207 offset:57344
	v_mfma_f32_16x16x32_bf16 v[62:65], v[158:161], v[66:69], 0
	ds_read_b128 v[158:161], v207 offset:61440
	s_waitcnt lgkmcnt(8)
	v_mfma_f32_16x16x32_bf16 v[2:5], v[98:101], v[70:73], v[2:5]
	ds_read_b128 v[98:101], v208 offset:0
	v_mfma_f32_16x16x32_bf16 v[6:9], v[102:105], v[70:73], v[6:9]
	ds_read_b128 v[102:105], v208 offset:4096
	v_mfma_f32_16x16x32_bf16 v[10:13], v[106:109], v[70:73], v[10:13]
	ds_read_b128 v[106:109], v208 offset:8192
	v_mfma_f32_16x16x32_bf16 v[14:17], v[110:113], v[70:73], v[14:17]
	ds_read_b128 v[110:113], v208 offset:12288
	v_mfma_f32_16x16x32_bf16 v[18:21], v[114:117], v[70:73], v[18:21]
	ds_read_b128 v[114:117], v208 offset:16384
	v_mfma_f32_16x16x32_bf16 v[22:25], v[118:121], v[70:73], v[22:25]
	ds_read_b128 v[118:121], v208 offset:20480
	v_mfma_f32_16x16x32_bf16 v[26:29], v[122:125], v[70:73], v[26:29]
	ds_read_b128 v[122:125], v208 offset:24576
	v_mfma_f32_16x16x32_bf16 v[30:33], v[126:129], v[70:73], v[30:33]
	ds_read_b128 v[126:129], v208 offset:28672
	s_waitcnt lgkmcnt(8)
	v_mfma_f32_16x16x32_bf16 v[34:37], v[130:133], v[70:73], v[34:37]
	ds_read_b128 v[130:133], v208 offset:32768
	v_mfma_f32_16x16x32_bf16 v[38:41], v[134:137], v[70:73], v[38:41]
	ds_read_b128 v[134:137], v208 offset:36864
	v_mfma_f32_16x16x32_bf16 v[42:45], v[138:141], v[70:73], v[42:45]
	ds_read_b128 v[138:141], v208 offset:40960
	v_mfma_f32_16x16x32_bf16 v[46:49], v[142:145], v[70:73], v[46:49]
	ds_read_b128 v[142:145], v208 offset:45056
	v_mfma_f32_16x16x32_bf16 v[50:53], v[146:149], v[70:73], v[50:53]
	ds_read_b128 v[146:149], v208 offset:49152
	v_mfma_f32_16x16x32_bf16 v[54:57], v[150:153], v[70:73], v[54:57]
	ds_read_b128 v[150:153], v208 offset:53248
	v_mfma_f32_16x16x32_bf16 v[58:61], v[154:157], v[70:73], v[58:61]
	ds_read_b128 v[154:157], v208 offset:57344
	v_mfma_f32_16x16x32_bf16 v[62:65], v[158:161], v[70:73], v[62:65]
	ds_read_b128 v[158:161], v208 offset:61440
	s_waitcnt lgkmcnt(8)
	v_mfma_f32_16x16x32_bf16 v[2:5], v[98:101], v[74:77], v[2:5]
	ds_read_b128 v[98:101], v209 offset:0
	v_mfma_f32_16x16x32_bf16 v[6:9], v[102:105], v[74:77], v[6:9]
	ds_read_b128 v[102:105], v209 offset:4096
	v_mfma_f32_16x16x32_bf16 v[10:13], v[106:109], v[74:77], v[10:13]
	ds_read_b128 v[106:109], v209 offset:8192
	v_mfma_f32_16x16x32_bf16 v[14:17], v[110:113], v[74:77], v[14:17]
	ds_read_b128 v[110:113], v209 offset:12288
	v_mfma_f32_16x16x32_bf16 v[18:21], v[114:117], v[74:77], v[18:21]
	ds_read_b128 v[114:117], v209 offset:16384
	v_mfma_f32_16x16x32_bf16 v[22:25], v[118:121], v[74:77], v[22:25]
	ds_read_b128 v[118:121], v209 offset:20480
	v_mfma_f32_16x16x32_bf16 v[26:29], v[122:125], v[74:77], v[26:29]
	ds_read_b128 v[122:125], v209 offset:24576
	v_mfma_f32_16x16x32_bf16 v[30:33], v[126:129], v[74:77], v[30:33]
	ds_read_b128 v[126:129], v209 offset:28672
	s_waitcnt lgkmcnt(8)
; #define LAS __attribute__((address_space(3)))
; #define MFMA16(a, b, c) __builtin_amdgcn_mfma_f32_16x16x32_bf16((a), (b), (c), 0, 0, 0)
; #define XK_LOAD(R, b_, h_, hh_) do { _Pragma("unroll") for (int i = 0; i < 8; ++i) { const int p = tid + 512 * i, m = p >> 4, cb = p & 15; R[i] = *(const u32x4*)(memK + (size_t)((b_) * NMEM + m) * D + (h_) * 256 + 128 * (hh_) + 8 * cb); } } while (0)
; #define XV_LOAD(R, b_, h_, hh_) do { _Pragma("unroll") for (int i = 0; i < 8; ++i) { const int p = tid + 512 * i, dhr = p >> 5, c = p & 31; R[i] = *(const u32x4*)(memVT + (size_t)((h_) * 256 + 128 * (hh_) + dhr) * MROWS + (b_) * NMEM + 8 * c); } } while (0)
; #define XV_WRITE(R) do { _Pragma("unroll") for (int i = 0; i < 8; ++i) { const int p = tid + 512 * i, dhr = p >> 5, c = p & 31; u32x2 lo, hi; lo.x = R[i].x; lo.y = R[i].y; hi.x = R[i].z; hi.y = R[i].w; \
;         *(LAS u32x2*)(VL + vt_off(dhr, 2 * c)) = lo; *(LAS u32x2*)(VL + vt_off(dhr, 2 * c + 1)) = hi; } } while (0)
; DI void xattn_phase(LAS unsigned char* L, const bf16* Qx, const bf16* memK, const bf16* memVT, bf16* Ox, int G, int bid, int tid, unsigned long long& tsec) {
;     ...
;             if (hh == 0) { XV_WRITE(rb); XK_LOAD(ra, b, h, 1); XV_LOAD(rb, b, h, 1); }
;     ...
;             for (int k4 = 0; k4 < 4; ++k4) { const bf16x8 qk = *(const bf16x8*)(Qx + tq * D + h * 256 + 128 * hh + 32 * k4 + 8 * fq);
; #pragma unroll
;                 for (int k8 = 0; k8 < 4; ++k8) { bf16x8 av[4];
; #pragma unroll
;                     for (int kt = 0; kt < 4; ++kt) av[kt] = *(const LAS bf16x8*)(KL + (16 * (4 * k8 + kt) + fr) * KSTR + (32 * k4 + 8 * fq) * 2);
; #pragma unroll
;                     for (int kt = 0; kt < 4; ++kt) s[4 * k8 + kt] = MFMA16(av[kt], qk, s[4 * k8 + kt]); } }
	v_mfma_f32_16x16x32_bf16 v[34:37], v[130:133], v[74:77], v[34:37]
	ds_read_b128 v[130:133], v209 offset:32768
	v_mfma_f32_16x16x32_bf16 v[38:41], v[134:137], v[74:77], v[38:41]
	ds_read_b128 v[134:137], v209 offset:36864
	v_mfma_f32_16x16x32_bf16 v[42:45], v[138:141], v[74:77], v[42:45]
	ds_read_b128 v[138:141], v209 offset:40960
	v_mfma_f32_16x16x32_bf16 v[46:49], v[142:145], v[74:77], v[46:49]
	ds_read_b128 v[142:145], v209 offset:45056
	v_mfma_f32_16x16x32_bf16 v[50:53], v[146:149], v[74:77], v[50:53]
	ds_read_b128 v[146:149], v209 offset:49152
	v_mfma_f32_16x16x32_bf16 v[54:57], v[150:153], v[74:77], v[54:57]
	ds_read_b128 v[150:153], v209 offset:53248
	v_mfma_f32_16x16x32_bf16 v[58:61], v[154:157], v[74:77], v[58:61]
	ds_read_b128 v[154:157], v209 offset:57344
	v_mfma_f32_16x16x32_bf16 v[62:65], v[158:161], v[74:77], v[62:65]
	ds_read_b128 v[158:161], v209 offset:61440
	s_waitcnt lgkmcnt(8)
	v_mfma_f32_16x16x32_bf16 v[2:5], v[98:101], v[78:81], v[2:5]
	v_mfma_f32_16x16x32_bf16 v[6:9], v[102:105], v[78:81], v[6:9]
	v_mfma_f32_16x16x32_bf16 v[10:13], v[106:109], v[78:81], v[10:13]
	v_mfma_f32_16x16x32_bf16 v[14:17], v[110:113], v[78:81], v[14:17]
	v_mfma_f32_16x16x32_bf16 v[18:21], v[114:117], v[78:81], v[18:21]
	v_mfma_f32_16x16x32_bf16 v[22:25], v[118:121], v[78:81], v[22:25]
	v_mfma_f32_16x16x32_bf16 v[26:29], v[122:125], v[78:81], v[26:29]
	v_mfma_f32_16x16x32_bf16 v[30:33], v[126:129], v[78:81], v[30:33]
	s_waitcnt lgkmcnt(0)
	v_mfma_f32_16x16x32_bf16 v[34:37], v[130:133], v[78:81], v[34:37]
	v_mfma_f32_16x16x32_bf16 v[38:41], v[134:137], v[78:81], v[38:41]
	v_mfma_f32_16x16x32_bf16 v[42:45], v[138:141], v[78:81], v[42:45]
	v_mfma_f32_16x16x32_bf16 v[46:49], v[142:145], v[78:81], v[46:49]
	v_mfma_f32_16x16x32_bf16 v[50:53], v[146:149], v[78:81], v[50:53]
	v_mfma_f32_16x16x32_bf16 v[54:57], v[150:153], v[78:81], v[54:57]
	v_mfma_f32_16x16x32_bf16 v[58:61], v[154:157], v[78:81], v[58:61]
	v_mfma_f32_16x16x32_bf16 v[62:65], v[158:161], v[78:81], v[62:65]
	s_waitcnt vmcnt(0)
	s_barrier
	s_add_u32 s44, s42, 0
	s_addc_u32 s45, s43, 0
	v_lshrrev_b32_e32 v237, 5, v236
	v_add_u32_e32 v237, 0, v237
	v_and_b32_e32 v248, 31, v236
	v_xor_b32_e32 v248, v248, v237
	v_lshl_add_u32 v237, s16, 4, v237
	v_lshlrev_b32_e32 v237, 11, v237
	v_lshl_add_u32 v237, v248, 4, v237
	s_add_u32 m0, s49, 0
	s_nop 0
	global_load_lds_dwordx4 v237, s[44:45]
	v_lshrrev_b32_e32 v237, 5, v236
	v_add_u32_e32 v237, 2, v237
	v_and_b32_e32 v248, 31, v236
	v_xor_b32_e32 v248, v248, v237
	v_lshl_add_u32 v237, s16, 4, v237
	v_lshlrev_b32_e32 v237, 11, v237
	v_lshl_add_u32 v237, v248, 4, v237
	s_add_u32 m0, s49, 1024
	s_nop 0
	global_load_lds_dwordx4 v237, s[44:45]
	v_lshrrev_b32_e32 v237, 5, v236
	v_add_u32_e32 v237, 4, v237
	v_and_b32_e32 v248, 31, v236
	v_xor_b32_e32 v248, v248, v237
	v_lshl_add_u32 v237, s16, 4, v237
	v_lshlrev_b32_e32 v237, 11, v237
	v_lshl_add_u32 v237, v248, 4, v237
	s_add_u32 m0, s49, 2048
	s_nop 0
	global_load_lds_dwordx4 v237, s[44:45]
	v_lshrrev_b32_e32 v237, 5, v236
	v_add_u32_e32 v237, 6, v237
	v_and_b32_e32 v248, 31, v236
	v_xor_b32_e32 v248, v248, v237
	v_lshl_add_u32 v237, s16, 4, v237
	v_lshlrev_b32_e32 v237, 11, v237
	v_lshl_add_u32 v237, v248, 4, v237
	s_add_u32 m0, s49, 3072
	s_nop 0
	global_load_lds_dwordx4 v237, s[44:45]
	v_lshrrev_b32_e32 v237, 5, v236
	v_add_u32_e32 v237, 8, v237
	v_and_b32_e32 v248, 31, v236
	v_xor_b32_e32 v248, v248, v237
	v_lshl_add_u32 v237, s16, 4, v237
	v_lshlrev_b32_e32 v237, 11, v237
	v_lshl_add_u32 v237, v248, 4, v237
	s_add_u32 m0, s49, 4096
	s_nop 0
	global_load_lds_dwordx4 v237, s[44:45]
	v_lshrrev_b32_e32 v237, 5, v236
	v_add_u32_e32 v237, 10, v237
	v_and_b32_e32 v248, 31, v236
	v_xor_b32_e32 v248, v248, v237
	v_lshl_add_u32 v237, s16, 4, v237
	v_lshlrev_b32_e32 v237, 11, v237
	v_lshl_add_u32 v237, v248, 4, v237
	s_add_u32 m0, s49, 5120
	s_nop 0
	global_load_lds_dwordx4 v237, s[44:45]
	v_lshrrev_b32_e32 v237, 5, v236
	v_add_u32_e32 v237, 12, v237
	v_and_b32_e32 v248, 31, v236
	v_xor_b32_e32 v248, v248, v237
	v_lshl_add_u32 v237, s16, 4, v237
	v_lshlrev_b32_e32 v237, 11, v237
	v_lshl_add_u32 v237, v248, 4, v237
	s_add_u32 m0, s49, 6144
	s_nop 0
	global_load_lds_dwordx4 v237, s[44:45]
	v_lshrrev_b32_e32 v237, 5, v236
	v_add_u32_e32 v237, 14, v237
	v_and_b32_e32 v248, 31, v236
	v_xor_b32_e32 v248, v248, v237
	v_lshl_add_u32 v237, s16, 4, v237
	v_lshlrev_b32_e32 v237, 11, v237
	v_lshl_add_u32 v237, v248, 4, v237
	s_add_u32 m0, s49, 7168
	s_nop 0
	global_load_lds_dwordx4 v237, s[44:45]
	ds_read_b128 v[98:101], v212 offset:0
	ds_read_b128 v[102:105], v212 offset:4096
	ds_read_b128 v[106:109], v212 offset:8192
	ds_read_b128 v[110:113], v212 offset:12288
	ds_read_b128 v[114:117], v212 offset:16384
	ds_read_b128 v[118:121], v212 offset:20480
	ds_read_b128 v[122:125], v212 offset:24576
	ds_read_b128 v[126:129], v212 offset:28672
	ds_read_b128 v[130:133], v212 offset:32768
	ds_read_b128 v[134:137], v212 offset:36864
	ds_read_b128 v[138:141], v212 offset:40960
	ds_read_b128 v[142:145], v212 offset:45056
	ds_read_b128 v[146:149], v212 offset:49152
	ds_read_b128 v[150:153], v212 offset:53248
	ds_read_b128 v[154:157], v212 offset:57344
	ds_read_b128 v[158:161], v212 offset:61440
	s_waitcnt lgkmcnt(8)
; #define LAS __attribute__((address_space(3)))
; #define MFMA16(a, b, c) __builtin_amdgcn_mfma_f32_16x16x32_bf16((a), (b), (c), 0, 0, 0)
; DI void xattn_phase(LAS unsigned char* L, const bf16* Qx, const bf16* memK, const bf16* memVT, bf16* Ox, int G, int bid, int tid, unsigned long long& tsec) {
;     ...
;             for (int k4 = 0; k4 < 4; ++k4) { const bf16x8 qk = *(const bf16x8*)(Qx + tq * D + h * 256 + 128 * hh + 32 * k4 + 8 * fq);
; #pragma unroll
;                 for (int k8 = 0; k8 < 4; ++k8) { bf16x8 av[4];
; #pragma unroll
;                     for (int kt = 0; kt < 4; ++kt) av[kt] = *(const LAS bf16x8*)(KL + (16 * (4 * k8 + kt) + fr) * KSTR + (32 * k4 + 8 * fq) * 2);
; #pragma unroll
;                     for (int kt = 0; kt < 4; ++kt) s[4 * k8 + kt] = MFMA16(av[kt], qk, s[4 * k8 + kt]); } }
	v_mfma_f32_16x16x32_bf16 v[2:5], v[98:101], v[82:85], v[2:5]
	ds_read_b128 v[98:101], v213 offset:0
	v_mfma_f32_16x16x32_bf16 v[6:9], v[102:105], v[82:85], v[6:9]
	ds_read_b128 v[102:105], v213 offset:4096
	v_mfma_f32_16x16x32_bf16 v[10:13], v[106:109], v[82:85], v[10:13]
	ds_read_b128 v[106:109], v213 offset:8192
	v_mfma_f32_16x16x32_bf16 v[14:17], v[110:113], v[82:85], v[14:17]
	ds_read_b128 v[110:113], v213 offset:12288
	v_mfma_f32_16x16x32_bf16 v[18:21], v[114:117], v[82:85], v[18:21]
	ds_read_b128 v[114:117], v213 offset:16384
	v_mfma_f32_16x16x32_bf16 v[22:25], v[118:121], v[82:85], v[22:25]
	ds_read_b128 v[118:121], v213 offset:20480
	v_mfma_f32_16x16x32_bf16 v[26:29], v[122:125], v[82:85], v[26:29]
	ds_read_b128 v[122:125], v213 offset:24576
	v_mfma_f32_16x16x32_bf16 v[30:33], v[126:129], v[82:85], v[30:33]
	ds_read_b128 v[126:129], v213 offset:28672
	s_waitcnt lgkmcnt(8)
	v_mfma_f32_16x16x32_bf16 v[34:37], v[130:133], v[82:85], v[34:37]
	ds_read_b128 v[130:133], v213 offset:32768
	v_mfma_f32_16x16x32_bf16 v[38:41], v[134:137], v[82:85], v[38:41]
	ds_read_b128 v[134:137], v213 offset:36864
	v_mfma_f32_16x16x32_bf16 v[42:45], v[138:141], v[82:85], v[42:45]
	ds_read_b128 v[138:141], v213 offset:40960
	v_mfma_f32_16x16x32_bf16 v[46:49], v[142:145], v[82:85], v[46:49]
	ds_read_b128 v[142:145], v213 offset:45056
	v_mfma_f32_16x16x32_bf16 v[50:53], v[146:149], v[82:85], v[50:53]
	ds_read_b128 v[146:149], v213 offset:49152
	v_mfma_f32_16x16x32_bf16 v[54:57], v[150:153], v[82:85], v[54:57]
	ds_read_b128 v[150:153], v213 offset:53248
	v_mfma_f32_16x16x32_bf16 v[58:61], v[154:157], v[82:85], v[58:61]
	ds_read_b128 v[154:157], v213 offset:57344
	v_mfma_f32_16x16x32_bf16 v[62:65], v[158:161], v[82:85], v[62:65]
	ds_read_b128 v[158:161], v213 offset:61440
	s_waitcnt lgkmcnt(8)
	v_mfma_f32_16x16x32_bf16 v[2:5], v[98:101], v[86:89], v[2:5]
	ds_read_b128 v[98:101], v214 offset:0
	v_mfma_f32_16x16x32_bf16 v[6:9], v[102:105], v[86:89], v[6:9]
	ds_read_b128 v[102:105], v214 offset:4096
	v_mfma_f32_16x16x32_bf16 v[10:13], v[106:109], v[86:89], v[10:13]
	ds_read_b128 v[106:109], v214 offset:8192
	v_mfma_f32_16x16x32_bf16 v[14:17], v[110:113], v[86:89], v[14:17]
	ds_read_b128 v[110:113], v214 offset:12288
	v_mfma_f32_16x16x32_bf16 v[18:21], v[114:117], v[86:89], v[18:21]
	ds_read_b128 v[114:117], v214 offset:16384
	v_mfma_f32_16x16x32_bf16 v[22:25], v[118:121], v[86:89], v[22:25]
	ds_read_b128 v[118:121], v214 offset:20480
	v_mfma_f32_16x16x32_bf16 v[26:29], v[122:125], v[86:89], v[26:29]
	ds_read_b128 v[122:125], v214 offset:24576
	v_mfma_f32_16x16x32_bf16 v[30:33], v[126:129], v[86:89], v[30:33]
	ds_read_b128 v[126:129], v214 offset:28672
	s_waitcnt lgkmcnt(8)
	v_mfma_f32_16x16x32_bf16 v[34:37], v[130:133], v[86:89], v[34:37]
	ds_read_b128 v[130:133], v214 offset:32768
	v_mfma_f32_16x16x32_bf16 v[38:41], v[134:137], v[86:89], v[38:41]
	ds_read_b128 v[134:137], v214 offset:36864
	v_mfma_f32_16x16x32_bf16 v[42:45], v[138:141], v[86:89], v[42:45]
	ds_read_b128 v[138:141], v214 offset:40960
	v_mfma_f32_16x16x32_bf16 v[46:49], v[142:145], v[86:89], v[46:49]
	ds_read_b128 v[142:145], v214 offset:45056
	v_mfma_f32_16x16x32_bf16 v[50:53], v[146:149], v[86:89], v[50:53]
	ds_read_b128 v[146:149], v214 offset:49152
	v_mfma_f32_16x16x32_bf16 v[54:57], v[150:153], v[86:89], v[54:57]
	ds_read_b128 v[150:153], v214 offset:53248
	v_mfma_f32_16x16x32_bf16 v[58:61], v[154:157], v[86:89], v[58:61]
	ds_read_b128 v[154:157], v214 offset:57344
	v_mfma_f32_16x16x32_bf16 v[62:65], v[158:161], v[86:89], v[62:65]
	ds_read_b128 v[158:161], v214 offset:61440
	s_waitcnt lgkmcnt(8)
	v_mfma_f32_16x16x32_bf16 v[2:5], v[98:101], v[90:93], v[2:5]
	ds_read_b128 v[98:101], v215 offset:0
	v_mfma_f32_16x16x32_bf16 v[6:9], v[102:105], v[90:93], v[6:9]
	ds_read_b128 v[102:105], v215 offset:4096
	v_mfma_f32_16x16x32_bf16 v[10:13], v[106:109], v[90:93], v[10:13]
	ds_read_b128 v[106:109], v215 offset:8192
	v_mfma_f32_16x16x32_bf16 v[14:17], v[110:113], v[90:93], v[14:17]
	ds_read_b128 v[110:113], v215 offset:12288
	v_mfma_f32_16x16x32_bf16 v[18:21], v[114:117], v[90:93], v[18:21]
	ds_read_b128 v[114:117], v215 offset:16384
	v_mfma_f32_16x16x32_bf16 v[22:25], v[118:121], v[90:93], v[22:25]
	ds_read_b128 v[118:121], v215 offset:20480
	v_mfma_f32_16x16x32_bf16 v[26:29], v[122:125], v[90:93], v[26:29]
	ds_read_b128 v[122:125], v215 offset:24576
	v_mfma_f32_16x16x32_bf16 v[30:33], v[126:129], v[90:93], v[30:33]
	ds_read_b128 v[126:129], v215 offset:28672
	s_waitcnt lgkmcnt(8)
	v_mfma_f32_16x16x32_bf16 v[34:37], v[130:133], v[90:93], v[34:37]
	ds_read_b128 v[130:133], v215 offset:32768
	v_mfma_f32_16x16x32_bf16 v[38:41], v[134:137], v[90:93], v[38:41]
	ds_read_b128 v[134:137], v215 offset:36864
	v_mfma_f32_16x16x32_bf16 v[42:45], v[138:141], v[90:93], v[42:45]
	ds_read_b128 v[138:141], v215 offset:40960
	v_mfma_f32_16x16x32_bf16 v[46:49], v[142:145], v[90:93], v[46:49]
	ds_read_b128 v[142:145], v215 offset:45056
	v_mfma_f32_16x16x32_bf16 v[50:53], v[146:149], v[90:93], v[50:53]
	ds_read_b128 v[146:149], v215 offset:49152
	v_mfma_f32_16x16x32_bf16 v[54:57], v[150:153], v[90:93], v[54:57]
	ds_read_b128 v[150:153], v215 offset:53248
	v_mfma_f32_16x16x32_bf16 v[58:61], v[154:157], v[90:93], v[58:61]
	ds_read_b128 v[154:157], v215 offset:57344
	v_mfma_f32_16x16x32_bf16 v[62:65], v[158:161], v[90:93], v[62:65]
	ds_read_b128 v[158:161], v215 offset:61440
	s_waitcnt lgkmcnt(8)
; DI void xattn_phase(LAS unsigned char* L, const bf16* Qx, const bf16* memK, const bf16* memVT, bf16* Ox, int G, int bid, int tid, unsigned long long& tsec) {
;     ...
;         float mx = -INFINITY;
; #pragma unroll
;         for (int kt = 0; kt < 16; ++kt)
; #pragma unroll
;             for (int e = 0; e < 4; ++e) { const float v = s[kt][e] * 0.0625f; s[kt][e] = v; mx = fmaxf(mx, v); }
;         mx = fmaxf(mx, __shfl_xor(mx, 16)); mx = fmaxf(mx, __shfl_xor(mx, 32));
;         float den = 0.f;
; #pragma unroll
;         for (int kt = 0; kt < 16; ++kt)
; #pragma unroll
;             for (int e = 0; e < 4; ++e) { const float p = __expf(s[kt][e] - mx); s[kt][e] = p; den += p; }
	v_mfma_f32_16x16x32_bf16 v[2:5], v[98:101], v[94:97], v[2:5]
	v_mfma_f32_16x16x32_bf16 v[6:9], v[102:105], v[94:97], v[6:9]
	v_mfma_f32_16x16x32_bf16 v[10:13], v[106:109], v[94:97], v[10:13]
	v_mfma_f32_16x16x32_bf16 v[14:17], v[110:113], v[94:97], v[14:17]
	v_mfma_f32_16x16x32_bf16 v[18:21], v[114:117], v[94:97], v[18:21]
	v_mfma_f32_16x16x32_bf16 v[22:25], v[118:121], v[94:97], v[22:25]
	v_mfma_f32_16x16x32_bf16 v[26:29], v[122:125], v[94:97], v[26:29]
	v_mfma_f32_16x16x32_bf16 v[30:33], v[126:129], v[94:97], v[30:33]
	s_waitcnt lgkmcnt(0)
	v_mfma_f32_16x16x32_bf16 v[34:37], v[130:133], v[94:97], v[34:37]
	v_mfma_f32_16x16x32_bf16 v[38:41], v[134:137], v[94:97], v[38:41]
	v_mfma_f32_16x16x32_bf16 v[42:45], v[138:141], v[94:97], v[42:45]
	v_mfma_f32_16x16x32_bf16 v[46:49], v[142:145], v[94:97], v[46:49]
	v_mfma_f32_16x16x32_bf16 v[50:53], v[146:149], v[94:97], v[50:53]
	v_mfma_f32_16x16x32_bf16 v[54:57], v[150:153], v[94:97], v[54:57]
	v_mfma_f32_16x16x32_bf16 v[58:61], v[154:157], v[94:97], v[58:61]
	v_mfma_f32_16x16x32_bf16 v[62:65], v[158:161], v[94:97], v[62:65]
	v_max_f32_e32 v249, v2, v3
	v_max3_f32 v249, v249, v4, v5
	v_max3_f32 v249, v249, v6, v7
	v_max3_f32 v249, v249, v8, v9
	v_max3_f32 v249, v249, v10, v11
	v_max3_f32 v249, v249, v12, v13
	v_max3_f32 v249, v249, v14, v15
	v_max3_f32 v249, v249, v16, v17
	v_max3_f32 v249, v249, v18, v19
	v_max3_f32 v249, v249, v20, v21
	v_max3_f32 v249, v249, v22, v23
	v_max3_f32 v249, v249, v24, v25
	v_max3_f32 v249, v249, v26, v27
	v_max3_f32 v249, v249, v28, v29
	v_max3_f32 v249, v249, v30, v31
	v_max3_f32 v249, v249, v32, v33
	v_max3_f32 v249, v249, v34, v35
	v_max3_f32 v249, v249, v36, v37
	v_max3_f32 v249, v249, v38, v39
	v_max3_f32 v249, v249, v40, v41
	v_max3_f32 v249, v249, v42, v43
	v_max3_f32 v249, v249, v44, v45
	v_max3_f32 v249, v249, v46, v47
	v_max3_f32 v249, v249, v48, v49
	v_max3_f32 v249, v249, v50, v51
	v_max3_f32 v249, v249, v52, v53
	v_max3_f32 v249, v249, v54, v55
	v_max3_f32 v249, v249, v56, v57
	v_max3_f32 v249, v249, v58, v59
	v_max3_f32 v249, v249, v60, v61
	v_max3_f32 v249, v249, v62, v63
	v_max3_f32 v249, v249, v64, v65
	ds_bpermute_b32 v237, v234, v249
	s_waitcnt lgkmcnt(0)
	v_max_f32_e32 v237, v237, v237
	v_max_f32_e32 v249, v249, v237
	ds_bpermute_b32 v237, v235, v249
	s_waitcnt lgkmcnt(0)
	v_max_f32_e32 v237, v237, v237
	v_max_f32_e32 v249, v249, v237
	v_mov_b32_e32 v162, 0x3db8aa3b
	v_mul_f32_e32 v164, v162, v249
	v_pk_fma_f32 v[2:3], v[2:3], v[162:163], v[164:165] op_sel_hi:[1,0,0] neg_lo:[0,0,1] neg_hi:[0,0,1]
	v_pk_fma_f32 v[4:5], v[4:5], v[162:163], v[164:165] op_sel_hi:[1,0,0] neg_lo:[0,0,1] neg_hi:[0,0,1]
	v_pk_fma_f32 v[6:7], v[6:7], v[162:163], v[164:165] op_sel_hi:[1,0,0] neg_lo:[0,0,1] neg_hi:[0,0,1]
	v_pk_fma_f32 v[8:9], v[8:9], v[162:163], v[164:165] op_sel_hi:[1,0,0] neg_lo:[0,0,1] neg_hi:[0,0,1]
	v_pk_fma_f32 v[10:11], v[10:11], v[162:163], v[164:165] op_sel_hi:[1,0,0] neg_lo:[0,0,1] neg_hi:[0,0,1]
	v_pk_fma_f32 v[12:13], v[12:13], v[162:163], v[164:165] op_sel_hi:[1,0,0] neg_lo:[0,0,1] neg_hi:[0,0,1]
	v_pk_fma_f32 v[14:15], v[14:15], v[162:163], v[164:165] op_sel_hi:[1,0,0] neg_lo:[0,0,1] neg_hi:[0,0,1]
	v_pk_fma_f32 v[16:17], v[16:17], v[162:163], v[164:165] op_sel_hi:[1,0,0] neg_lo:[0,0,1] neg_hi:[0,0,1]
	v_pk_fma_f32 v[18:19], v[18:19], v[162:163], v[164:165] op_sel_hi:[1,0,0] neg_lo:[0,0,1] neg_hi:[0,0,1]
	v_pk_fma_f32 v[20:21], v[20:21], v[162:163], v[164:165] op_sel_hi:[1,0,0] neg_lo:[0,0,1] neg_hi:[0,0,1]
	v_pk_fma_f32 v[22:23], v[22:23], v[162:163], v[164:165] op_sel_hi:[1,0,0] neg_lo:[0,0,1] neg_hi:[0,0,1]
	v_pk_fma_f32 v[24:25], v[24:25], v[162:163], v[164:165] op_sel_hi:[1,0,0] neg_lo:[0,0,1] neg_hi:[0,0,1]
	v_pk_fma_f32 v[26:27], v[26:27], v[162:163], v[164:165] op_sel_hi:[1,0,0] neg_lo:[0,0,1] neg_hi:[0,0,1]
	v_pk_fma_f32 v[28:29], v[28:29], v[162:163], v[164:165] op_sel_hi:[1,0,0] neg_lo:[0,0,1] neg_hi:[0,0,1]
	v_pk_fma_f32 v[30:31], v[30:31], v[162:163], v[164:165] op_sel_hi:[1,0,0] neg_lo:[0,0,1] neg_hi:[0,0,1]
	v_pk_fma_f32 v[32:33], v[32:33], v[162:163], v[164:165] op_sel_hi:[1,0,0] neg_lo:[0,0,1] neg_hi:[0,0,1]
	v_pk_fma_f32 v[34:35], v[34:35], v[162:163], v[164:165] op_sel_hi:[1,0,0] neg_lo:[0,0,1] neg_hi:[0,0,1]
	v_pk_fma_f32 v[36:37], v[36:37], v[162:163], v[164:165] op_sel_hi:[1,0,0] neg_lo:[0,0,1] neg_hi:[0,0,1]
	v_pk_fma_f32 v[38:39], v[38:39], v[162:163], v[164:165] op_sel_hi:[1,0,0] neg_lo:[0,0,1] neg_hi:[0,0,1]
	v_pk_fma_f32 v[40:41], v[40:41], v[162:163], v[164:165] op_sel_hi:[1,0,0] neg_lo:[0,0,1] neg_hi:[0,0,1]
	v_pk_fma_f32 v[42:43], v[42:43], v[162:163], v[164:165] op_sel_hi:[1,0,0] neg_lo:[0,0,1] neg_hi:[0,0,1]
	v_pk_fma_f32 v[44:45], v[44:45], v[162:163], v[164:165] op_sel_hi:[1,0,0] neg_lo:[0,0,1] neg_hi:[0,0,1]
	v_pk_fma_f32 v[46:47], v[46:47], v[162:163], v[164:165] op_sel_hi:[1,0,0] neg_lo:[0,0,1] neg_hi:[0,0,1]
	v_pk_fma_f32 v[48:49], v[48:49], v[162:163], v[164:165] op_sel_hi:[1,0,0] neg_lo:[0,0,1] neg_hi:[0,0,1]
	v_pk_fma_f32 v[50:51], v[50:51], v[162:163], v[164:165] op_sel_hi:[1,0,0] neg_lo:[0,0,1] neg_hi:[0,0,1]
	v_pk_fma_f32 v[52:53], v[52:53], v[162:163], v[164:165] op_sel_hi:[1,0,0] neg_lo:[0,0,1] neg_hi:[0,0,1]
	v_pk_fma_f32 v[54:55], v[54:55], v[162:163], v[164:165] op_sel_hi:[1,0,0] neg_lo:[0,0,1] neg_hi:[0,0,1]
	v_pk_fma_f32 v[56:57], v[56:57], v[162:163], v[164:165] op_sel_hi:[1,0,0] neg_lo:[0,0,1] neg_hi:[0,0,1]
	v_pk_fma_f32 v[58:59], v[58:59], v[162:163], v[164:165] op_sel_hi:[1,0,0] neg_lo:[0,0,1] neg_hi:[0,0,1]
	v_pk_fma_f32 v[60:61], v[60:61], v[162:163], v[164:165] op_sel_hi:[1,0,0] neg_lo:[0,0,1] neg_hi:[0,0,1]
	v_pk_fma_f32 v[62:63], v[62:63], v[162:163], v[164:165] op_sel_hi:[1,0,0] neg_lo:[0,0,1] neg_hi:[0,0,1]
; DI unsigned pk2(float lo, float hi) { const bf2_t r = __builtin_convertvector((f32x2_t){lo, hi}, bf2_t); return __builtin_bit_cast(unsigned, r); }
; #define DSEC(k) do { if (PROBE_DSEC) { const unsigned long long tn_ = __builtin_amdgcn_s_memrealtime(); if (PROBE_DSEC == (k)) tsec += tn_ - tl_; tl_ = tn_; } } while (0)
; DI void xattn_phase(LAS unsigned char* L, const bf16* Qx, const bf16* memK, const bf16* memVT, bf16* Ox, int G, int bid, int tid, unsigned long long& tsec) {
;     ...
;         for (int kt = 0; kt < 16; ++kt)
; #pragma unroll
;             for (int e = 0; e < 4; ++e) { const float p = __expf(s[kt][e] - mx); s[kt][e] = p; den += p; }
;         den += __shfl_xor(den, 16); den += __shfl_xor(den, 32);
;         DSEC(13);
;         bf16x8 pf[8];
; #pragma unroll
;         for (int pp = 0; pp < 8; ++pp) { u32x4 pw; pw.x = pk2(s[2 * pp][0], s[2 * pp][1]); pw.y = pk2(s[2 * pp][2], s[2 * pp][3]); pw.z = pk2(s[2 * pp + 1][0], s[2 * pp + 1][1]); pw.w = pk2(s[2 * pp + 1][2], s[2 * pp + 1][3]); pf[pp] = mk8(pw); }
;         const float inv = __builtin_amdgcn_rcpf(den);
	v_pk_fma_f32 v[64:65], v[64:65], v[162:163], v[164:165] op_sel_hi:[1,0,0] neg_lo:[0,0,1] neg_hi:[0,0,1]
	v_exp_f32_e32 v2, v2
	v_exp_f32_e32 v3, v3
	v_exp_f32_e32 v4, v4
	v_exp_f32_e32 v5, v5
	v_exp_f32_e32 v6, v6
	v_exp_f32_e32 v7, v7
	v_exp_f32_e32 v8, v8
	v_exp_f32_e32 v9, v9
	v_exp_f32_e32 v10, v10
	v_exp_f32_e32 v11, v11
	v_exp_f32_e32 v12, v12
	v_exp_f32_e32 v13, v13
	v_exp_f32_e32 v14, v14
	v_exp_f32_e32 v15, v15
	v_exp_f32_e32 v16, v16
	v_exp_f32_e32 v17, v17
	v_exp_f32_e32 v18, v18
	v_exp_f32_e32 v19, v19
	v_exp_f32_e32 v20, v20
	v_exp_f32_e32 v21, v21
	v_exp_f32_e32 v22, v22
	v_exp_f32_e32 v23, v23
	v_exp_f32_e32 v24, v24
	v_exp_f32_e32 v25, v25
	v_exp_f32_e32 v26, v26
	v_exp_f32_e32 v27, v27
	v_exp_f32_e32 v28, v28
	v_exp_f32_e32 v29, v29
	v_exp_f32_e32 v30, v30
	v_exp_f32_e32 v31, v31
	v_exp_f32_e32 v32, v32
	v_exp_f32_e32 v33, v33
	v_exp_f32_e32 v34, v34
	v_exp_f32_e32 v35, v35
	v_exp_f32_e32 v36, v36
	v_exp_f32_e32 v37, v37
	v_exp_f32_e32 v38, v38
	v_exp_f32_e32 v39, v39
	v_exp_f32_e32 v40, v40
	v_exp_f32_e32 v41, v41
	v_exp_f32_e32 v42, v42
	v_exp_f32_e32 v43, v43
	v_exp_f32_e32 v44, v44
	v_exp_f32_e32 v45, v45
	v_exp_f32_e32 v46, v46
	v_exp_f32_e32 v47, v47
	v_exp_f32_e32 v48, v48
	v_exp_f32_e32 v49, v49
	v_exp_f32_e32 v50, v50
	v_exp_f32_e32 v51, v51
	v_exp_f32_e32 v52, v52
	v_exp_f32_e32 v53, v53
	v_exp_f32_e32 v54, v54
	v_exp_f32_e32 v55, v55
	v_exp_f32_e32 v56, v56
	v_exp_f32_e32 v57, v57
	v_exp_f32_e32 v58, v58
	v_exp_f32_e32 v59, v59
	v_exp_f32_e32 v60, v60
	v_exp_f32_e32 v61, v61
	v_exp_f32_e32 v62, v62
	v_exp_f32_e32 v63, v63
	v_exp_f32_e32 v64, v64
	v_exp_f32_e32 v65, v65
	s_nop 0
	v_pk_add_f32 v[166:167], v[2:3], v[4:5]
	v_pk_add_f32 v[166:167], v[6:7], v[166:167]
	v_pk_add_f32 v[166:167], v[8:9], v[166:167]
	v_pk_add_f32 v[166:167], v[10:11], v[166:167]
	v_pk_add_f32 v[166:167], v[12:13], v[166:167]
	v_pk_add_f32 v[166:167], v[14:15], v[166:167]
	v_pk_add_f32 v[166:167], v[16:17], v[166:167]
	v_pk_add_f32 v[166:167], v[18:19], v[166:167]
	v_pk_add_f32 v[166:167], v[20:21], v[166:167]
	v_pk_add_f32 v[166:167], v[22:23], v[166:167]
	v_pk_add_f32 v[166:167], v[24:25], v[166:167]
	v_pk_add_f32 v[166:167], v[26:27], v[166:167]
	v_pk_add_f32 v[166:167], v[28:29], v[166:167]
	v_pk_add_f32 v[166:167], v[30:31], v[166:167]
	v_pk_add_f32 v[166:167], v[32:33], v[166:167]
	v_pk_add_f32 v[166:167], v[34:35], v[166:167]
	v_pk_add_f32 v[166:167], v[36:37], v[166:167]
	v_pk_add_f32 v[166:167], v[38:39], v[166:167]
	v_pk_add_f32 v[166:167], v[40:41], v[166:167]
	v_pk_add_f32 v[166:167], v[42:43], v[166:167]
	v_pk_add_f32 v[166:167], v[44:45], v[166:167]
	v_pk_add_f32 v[166:167], v[46:47], v[166:167]
	v_pk_add_f32 v[166:167], v[48:49], v[166:167]
	v_pk_add_f32 v[166:167], v[50:51], v[166:167]
	v_pk_add_f32 v[166:167], v[52:53], v[166:167]
	v_pk_add_f32 v[166:167], v[54:55], v[166:167]
	v_pk_add_f32 v[166:167], v[56:57], v[166:167]
	v_pk_add_f32 v[166:167], v[58:59], v[166:167]
	v_pk_add_f32 v[166:167], v[60:61], v[166:167]
	v_pk_add_f32 v[166:167], v[62:63], v[166:167]
	v_pk_add_f32 v[166:167], v[64:65], v[166:167]
	v_add_f32_e32 v237, v166, v167
	ds_bpermute_b32 v248, v234, v237
	s_waitcnt lgkmcnt(0)
	v_add_f32_e32 v237, v237, v248
	ds_bpermute_b32 v248, v235, v237
	s_waitcnt lgkmcnt(0)
	v_add_f32_e32 v237, v237, v248
	v_rcp_f32_e32 v0, v237
	v_cvt_pk_bf16_f32 v162, v2, v3
	v_cvt_pk_bf16_f32 v163, v4, v5
	v_cvt_pk_bf16_f32 v164, v6, v7
	v_cvt_pk_bf16_f32 v165, v8, v9
	v_cvt_pk_bf16_f32 v166, v10, v11
	v_cvt_pk_bf16_f32 v167, v12, v13
	v_cvt_pk_bf16_f32 v168, v14, v15
	v_cvt_pk_bf16_f32 v169, v16, v17
	v_cvt_pk_bf16_f32 v170, v18, v19
	v_cvt_pk_bf16_f32 v171, v20, v21
	v_cvt_pk_bf16_f32 v172, v22, v23
	v_cvt_pk_bf16_f32 v173, v24, v25
	v_cvt_pk_bf16_f32 v174, v26, v27
	v_cvt_pk_bf16_f32 v175, v28, v29
	v_cvt_pk_bf16_f32 v176, v30, v31
	v_cvt_pk_bf16_f32 v177, v32, v33
	v_cvt_pk_bf16_f32 v178, v34, v35
	v_cvt_pk_bf16_f32 v179, v36, v37
	v_cvt_pk_bf16_f32 v180, v38, v39
	v_cvt_pk_bf16_f32 v181, v40, v41
	v_cvt_pk_bf16_f32 v182, v42, v43
	v_cvt_pk_bf16_f32 v183, v44, v45
	v_cvt_pk_bf16_f32 v184, v46, v47
	v_cvt_pk_bf16_f32 v185, v48, v49
	v_cvt_pk_bf16_f32 v186, v50, v51
	v_cvt_pk_bf16_f32 v187, v52, v53
	v_cvt_pk_bf16_f32 v188, v54, v55
	v_cvt_pk_bf16_f32 v189, v56, v57
	v_cvt_pk_bf16_f32 v190, v58, v59
	v_cvt_pk_bf16_f32 v191, v60, v61
	v_cvt_pk_bf16_f32 v192, v62, v63
	v_cvt_pk_bf16_f32 v193, v64, v65
	s_waitcnt vmcnt(0)
	s_barrier
; #define LAS __attribute__((address_space(3)))
; #define MFMA16(a, b, c) __builtin_amdgcn_mfma_f32_16x16x32_bf16((a), (b), (c), 0, 0, 0)
; #define DSEC(k) do { if (PROBE_DSEC) { const unsigned long long tn_ = __builtin_amdgcn_s_memrealtime(); if (PROBE_DSEC == (k)) tsec += tn_ - tl_; tl_ = tn_; } } while (0)
; #define XV_LOAD(R, b_, h_, hh_) do { _Pragma("unroll") for (int i = 0; i < 8; ++i) { const int p = tid + 512 * i, dhr = p >> 5, c = p & 31; R[i] = *(const u32x4*)(memVT + (size_t)((h_) * 256 + 128 * (hh_) + dhr) * MROWS + (b_) * NMEM + 8 * c); } } while (0)
; #define XV_WRITE(R) do { _Pragma("unroll") for (int i = 0; i < 8; ++i) { const int p = tid + 512 * i, dhr = p >> 5, c = p & 31; u32x2 lo, hi; lo.x = R[i].x; lo.y = R[i].y; hi.x = R[i].z; hi.y = R[i].w; \
;         *(LAS u32x2*)(VL + vt_off(dhr, 2 * c)) = lo; *(LAS u32x2*)(VL + vt_off(dhr, 2 * c + 1)) = hi; } } while (0)
; DI void xattn_phase(LAS unsigned char* L, const bf16* Qx, const bf16* memK, const bf16* memVT, bf16* Ox, int G, int bid, int tid, unsigned long long& tsec) {
;     ...
; #pragma unroll
;         for (int hh = 0; hh < 2; ++hh) {
;             if (hh == 1) { DSEC(14); __syncthreads(); XV_WRITE(rb); XV_LOAD(rb, bn, hn, 0); __syncthreads(); DSEC(15); }
;             f32x4 o[8];
; #pragma unroll
;             for (int dt = 0; dt < 8; ++dt) o[dt] = (f32x4){0.f, 0.f, 0.f, 0.f};
;             const unsigned x0 = (unsigned)(fq ^ (fr >> 3));
;             const LAS unsigned char* vev = L + KL_BYTES + fr * VSTR + (x0 << 3); const LAS unsigned char* vod = L + KL_BYTES + fr * VSTR + ((x0 ^ 2u) << 3);
; #pragma unroll
;             for (int pp = 0; pp < 8; ++pp)
; #pragma unroll
;                 for (int d4 = 0; d4 < 2; ++d4) { bf16x8 vf[4];
; #pragma unroll
;                     for (int dq = 0; dq < 4; ++dq) { const int dt = 4 * d4 + dq; const LAS unsigned char* vb_ = ((dt & 1) ? vod : vev) + 16 * dt * VSTR + 64 * pp;
;                         const s16x4 lo = *(const LAS s16x4*)(vb_ + (((2 * dt) & 4) << 3)), hi = *(const LAS s16x4*)(vb_ + ((((2 * dt) & 4) ^ 4) << 3)); vf[dq] = __builtin_shufflevector(lo, hi, 0, 1, 2, 3, 4, 5, 6, 7); }
; #pragma unroll
;                     for (int dq = 0; dq < 4; ++dq) o[4 * d4 + dq] = MFMA16(vf[dq], pf[pp], o[4 * d4 + dq]);
	s_add_u32 s44, s42, 262144
	s_addc_u32 s45, s43, 0
	v_lshrrev_b32_e32 v237, 5, v236
	v_add_u32_e32 v237, 0, v237
	v_and_b32_e32 v248, 31, v236
	v_xor_b32_e32 v248, v248, v237
	v_lshl_add_u32 v237, s16, 4, v237
	v_lshlrev_b32_e32 v237, 11, v237
	v_lshl_add_u32 v237, v248, 4, v237
	s_add_u32 m0, s49, 65536
	s_nop 0
	global_load_lds_dwordx4 v237, s[44:45]
	v_lshrrev_b32_e32 v237, 5, v236
	v_add_u32_e32 v237, 2, v237
	v_and_b32_e32 v248, 31, v236
	v_xor_b32_e32 v248, v248, v237
	v_lshl_add_u32 v237, s16, 4, v237
	v_lshlrev_b32_e32 v237, 11, v237
	v_lshl_add_u32 v237, v248, 4, v237
	s_add_u32 m0, s49, 66560
	s_nop 0
	global_load_lds_dwordx4 v237, s[44:45]
	v_lshrrev_b32_e32 v237, 5, v236
	v_add_u32_e32 v237, 4, v237
	v_and_b32_e32 v248, 31, v236
	v_xor_b32_e32 v248, v248, v237
	v_lshl_add_u32 v237, s16, 4, v237
	v_lshlrev_b32_e32 v237, 11, v237
	v_lshl_add_u32 v237, v248, 4, v237
	s_add_u32 m0, s49, 67584
	s_nop 0
	global_load_lds_dwordx4 v237, s[44:45]
	v_lshrrev_b32_e32 v237, 5, v236
	v_add_u32_e32 v237, 6, v237
	v_and_b32_e32 v248, 31, v236
	v_xor_b32_e32 v248, v248, v237
	v_lshl_add_u32 v237, s16, 4, v237
	v_lshlrev_b32_e32 v237, 11, v237
	v_lshl_add_u32 v237, v248, 4, v237
	s_add_u32 m0, s49, 68608
	s_nop 0
	global_load_lds_dwordx4 v237, s[44:45]
	v_lshrrev_b32_e32 v237, 5, v236
	v_add_u32_e32 v237, 8, v237
	v_and_b32_e32 v248, 31, v236
	v_xor_b32_e32 v248, v248, v237
	v_lshl_add_u32 v237, s16, 4, v237
	v_lshlrev_b32_e32 v237, 11, v237
	v_lshl_add_u32 v237, v248, 4, v237
	s_add_u32 m0, s49, 69632
	s_nop 0
	global_load_lds_dwordx4 v237, s[44:45]
	v_lshrrev_b32_e32 v237, 5, v236
	v_add_u32_e32 v237, 10, v237
	v_and_b32_e32 v248, 31, v236
	v_xor_b32_e32 v248, v248, v237
	v_lshl_add_u32 v237, s16, 4, v237
	v_lshlrev_b32_e32 v237, 11, v237
	v_lshl_add_u32 v237, v248, 4, v237
	s_add_u32 m0, s49, 70656
	s_nop 0
	global_load_lds_dwordx4 v237, s[44:45]
	v_lshrrev_b32_e32 v237, 5, v236
	v_add_u32_e32 v237, 12, v237
	v_and_b32_e32 v248, 31, v236
	v_xor_b32_e32 v248, v248, v237
	v_lshl_add_u32 v237, s16, 4, v237
	v_lshlrev_b32_e32 v237, 11, v237
	v_lshl_add_u32 v237, v248, 4, v237
	s_add_u32 m0, s49, 71680
	s_nop 0
	global_load_lds_dwordx4 v237, s[44:45]
	v_lshrrev_b32_e32 v237, 5, v236
	v_add_u32_e32 v237, 14, v237
	v_and_b32_e32 v248, 31, v236
	v_xor_b32_e32 v248, v248, v237
	v_lshl_add_u32 v237, s16, 4, v237
	v_lshlrev_b32_e32 v237, 11, v237
	v_lshl_add_u32 v237, v248, 4, v237
	s_add_u32 m0, s49, 72704
	s_nop 0
	global_load_lds_dwordx4 v237, s[44:45]
	ds_read_b64 v[98:99], v216 offset:0
	ds_read_b64 v[100:101], v217 offset:0
	ds_read_b64 v[102:103], v216 offset:8192
	ds_read_b64 v[104:105], v217 offset:8192
	ds_read_b64 v[106:107], v216 offset:16384
	ds_read_b64 v[108:109], v217 offset:16384
	ds_read_b64 v[110:111], v216 offset:24576
	ds_read_b64 v[112:113], v217 offset:24576
	ds_read_b64 v[114:115], v216 offset:32768
	ds_read_b64 v[116:117], v217 offset:32768
	ds_read_b64 v[118:119], v216 offset:40960
	ds_read_b64 v[120:121], v217 offset:40960
	ds_read_b64 v[122:123], v216 offset:49152
	ds_read_b64 v[124:125], v217 offset:49152
	ds_read_b64 v[126:127], v216 offset:57344
	ds_read_b64 v[128:129], v217 offset:57344
	ds_read_b64 v[130:131], v218 offset:0
	ds_read_b64 v[132:133], v219 offset:0
	ds_read_b64 v[134:135], v218 offset:8192
	ds_read_b64 v[136:137], v219 offset:8192
	ds_read_b64 v[138:139], v218 offset:16384
	ds_read_b64 v[140:141], v219 offset:16384
	ds_read_b64 v[142:143], v218 offset:24576
	ds_read_b64 v[144:145], v219 offset:24576
	ds_read_b64 v[146:147], v218 offset:32768
	ds_read_b64 v[148:149], v219 offset:32768
	ds_read_b64 v[150:151], v218 offset:40960
	ds_read_b64 v[152:153], v219 offset:40960
	ds_read_b64 v[154:155], v218 offset:49152
	ds_read_b64 v[156:157], v219 offset:49152
	ds_read_b64 v[158:159], v218 offset:57344
	ds_read_b64 v[160:161], v219 offset:57344
	s_waitcnt lgkmcnt(15)
	v_mfma_f32_16x16x32_bf16 v[2:5], v[98:101], v[162:165], 0
	ds_read_b64 v[98:99], v220 offset:0
	ds_read_b64 v[100:101], v221 offset:0
	v_mfma_f32_16x16x32_bf16 v[6:9], v[102:105], v[162:165], 0
	ds_read_b64 v[102:103], v220 offset:8192
	ds_read_b64 v[104:105], v221 offset:8192
	v_mfma_f32_16x16x32_bf16 v[10:13], v[106:109], v[162:165], 0
	ds_read_b64 v[106:107], v220 offset:16384
	ds_read_b64 v[108:109], v221 offset:16384
	v_mfma_f32_16x16x32_bf16 v[14:17], v[110:113], v[162:165], 0
	ds_read_b64 v[110:111], v220 offset:24576
	ds_read_b64 v[112:113], v221 offset:24576
	v_mfma_f32_16x16x32_bf16 v[18:21], v[114:117], v[162:165], 0
	ds_read_b64 v[114:115], v220 offset:32768
	ds_read_b64 v[116:117], v221 offset:32768
	v_mfma_f32_16x16x32_bf16 v[22:25], v[118:121], v[162:165], 0
	ds_read_b64 v[118:119], v220 offset:40960
	ds_read_b64 v[120:121], v221 offset:40960
	v_mfma_f32_16x16x32_bf16 v[26:29], v[122:125], v[162:165], 0
	ds_read_b64 v[122:123], v220 offset:49152
	ds_read_b64 v[124:125], v221 offset:49152
	v_mfma_f32_16x16x32_bf16 v[30:33], v[126:129], v[162:165], 0
	ds_read_b64 v[126:127], v220 offset:57344
	ds_read_b64 v[128:129], v221 offset:57344
	s_waitcnt lgkmcnt(15)
; #define LAS __attribute__((address_space(3)))
; #define MFMA16(a, b, c) __builtin_amdgcn_mfma_f32_16x16x32_bf16((a), (b), (c), 0, 0, 0)
; DI void xattn_phase(LAS unsigned char* L, const bf16* Qx, const bf16* memK, const bf16* memVT, bf16* Ox, int G, int bid, int tid, unsigned long long& tsec) {
;     ...
;             for (int pp = 0; pp < 8; ++pp)
; #pragma unroll
;                 for (int d4 = 0; d4 < 2; ++d4) { bf16x8 vf[4];
; #pragma unroll
;                     for (int dq = 0; dq < 4; ++dq) { const int dt = 4 * d4 + dq; const LAS unsigned char* vb_ = ((dt & 1) ? vod : vev) + 16 * dt * VSTR + 64 * pp;
;                         const s16x4 lo = *(const LAS s16x4*)(vb_ + (((2 * dt) & 4) << 3)), hi = *(const LAS s16x4*)(vb_ + ((((2 * dt) & 4) ^ 4) << 3)); vf[dq] = __builtin_shufflevector(lo, hi, 0, 1, 2, 3, 4, 5, 6, 7); }
; #pragma unroll
;                     for (int dq = 0; dq < 4; ++dq) o[4 * d4 + dq] = MFMA16(vf[dq], pf[pp], o[4 * d4 + dq]);
;                 }
	v_mfma_f32_16x16x32_bf16 v[2:5], v[130:133], v[166:169], v[2:5]
	ds_read_b64 v[130:131], v222 offset:0
	ds_read_b64 v[132:133], v223 offset:0
	v_mfma_f32_16x16x32_bf16 v[6:9], v[134:137], v[166:169], v[6:9]
	ds_read_b64 v[134:135], v222 offset:8192
	ds_read_b64 v[136:137], v223 offset:8192
	v_mfma_f32_16x16x32_bf16 v[10:13], v[138:141], v[166:169], v[10:13]
	ds_read_b64 v[138:139], v222 offset:16384
	ds_read_b64 v[140:141], v223 offset:16384
	v_mfma_f32_16x16x32_bf16 v[14:17], v[142:145], v[166:169], v[14:17]
	ds_read_b64 v[142:143], v222 offset:24576
	ds_read_b64 v[144:145], v223 offset:24576
	v_mfma_f32_16x16x32_bf16 v[18:21], v[146:149], v[166:169], v[18:21]
	ds_read_b64 v[146:147], v222 offset:32768
	ds_read_b64 v[148:149], v223 offset:32768
	v_mfma_f32_16x16x32_bf16 v[22:25], v[150:153], v[166:169], v[22:25]
	ds_read_b64 v[150:151], v222 offset:40960
	ds_read_b64 v[152:153], v223 offset:40960
	v_mfma_f32_16x16x32_bf16 v[26:29], v[154:157], v[166:169], v[26:29]
	ds_read_b64 v[154:155], v222 offset:49152
	ds_read_b64 v[156:157], v223 offset:49152
	v_mfma_f32_16x16x32_bf16 v[30:33], v[158:161], v[166:169], v[30:33]
	ds_read_b64 v[158:159], v222 offset:57344
	ds_read_b64 v[160:161], v223 offset:57344
	s_waitcnt lgkmcnt(15)
	v_mfma_f32_16x16x32_bf16 v[2:5], v[98:101], v[170:173], v[2:5]
	ds_read_b64 v[98:99], v216 offset:256
	ds_read_b64 v[100:101], v217 offset:256
	v_mfma_f32_16x16x32_bf16 v[6:9], v[102:105], v[170:173], v[6:9]
	ds_read_b64 v[102:103], v216 offset:8448
	ds_read_b64 v[104:105], v217 offset:8448
	v_mfma_f32_16x16x32_bf16 v[10:13], v[106:109], v[170:173], v[10:13]
	ds_read_b64 v[106:107], v216 offset:16640
	ds_read_b64 v[108:109], v217 offset:16640
	v_mfma_f32_16x16x32_bf16 v[14:17], v[110:113], v[170:173], v[14:17]
	ds_read_b64 v[110:111], v216 offset:24832
	ds_read_b64 v[112:113], v217 offset:24832
	v_mfma_f32_16x16x32_bf16 v[18:21], v[114:117], v[170:173], v[18:21]
	ds_read_b64 v[114:115], v216 offset:33024
	ds_read_b64 v[116:117], v217 offset:33024
	v_mfma_f32_16x16x32_bf16 v[22:25], v[118:121], v[170:173], v[22:25]
	ds_read_b64 v[118:119], v216 offset:41216
	ds_read_b64 v[120:121], v217 offset:41216
	v_mfma_f32_16x16x32_bf16 v[26:29], v[122:125], v[170:173], v[26:29]
	ds_read_b64 v[122:123], v216 offset:49408
	ds_read_b64 v[124:125], v217 offset:49408
	v_mfma_f32_16x16x32_bf16 v[30:33], v[126:129], v[170:173], v[30:33]
	ds_read_b64 v[126:127], v216 offset:57600
	ds_read_b64 v[128:129], v217 offset:57600
	s_waitcnt lgkmcnt(15)
	v_mfma_f32_16x16x32_bf16 v[2:5], v[130:133], v[174:177], v[2:5]
	ds_read_b64 v[130:131], v218 offset:256
	ds_read_b64 v[132:133], v219 offset:256
	v_mfma_f32_16x16x32_bf16 v[6:9], v[134:137], v[174:177], v[6:9]
	ds_read_b64 v[134:135], v218 offset:8448
	ds_read_b64 v[136:137], v219 offset:8448
	v_mfma_f32_16x16x32_bf16 v[10:13], v[138:141], v[174:177], v[10:13]
	ds_read_b64 v[138:139], v218 offset:16640
	ds_read_b64 v[140:141], v219 offset:16640
	v_mfma_f32_16x16x32_bf16 v[14:17], v[142:145], v[174:177], v[14:17]
	ds_read_b64 v[142:143], v218 offset:24832
	ds_read_b64 v[144:145], v219 offset:24832
	v_mfma_f32_16x16x32_bf16 v[18:21], v[146:149], v[174:177], v[18:21]
	ds_read_b64 v[146:147], v218 offset:33024
	ds_read_b64 v[148:149], v219 offset:33024
	v_mfma_f32_16x16x32_bf16 v[22:25], v[150:153], v[174:177], v[22:25]
	ds_read_b64 v[150:151], v218 offset:41216
	ds_read_b64 v[152:153], v219 offset:41216
	v_mfma_f32_16x16x32_bf16 v[26:29], v[154:157], v[174:177], v[26:29]
	ds_read_b64 v[154:155], v218 offset:49408
	ds_read_b64 v[156:157], v219 offset:49408
	v_mfma_f32_16x16x32_bf16 v[30:33], v[158:161], v[174:177], v[30:33]
	ds_read_b64 v[158:159], v218 offset:57600
	ds_read_b64 v[160:161], v219 offset:57600
	s_waitcnt lgkmcnt(15)
	v_mfma_f32_16x16x32_bf16 v[2:5], v[98:101], v[178:181], v[2:5]
	ds_read_b64 v[98:99], v220 offset:256
	ds_read_b64 v[100:101], v221 offset:256
	v_mfma_f32_16x16x32_bf16 v[6:9], v[102:105], v[178:181], v[6:9]
	ds_read_b64 v[102:103], v220 offset:8448
	ds_read_b64 v[104:105], v221 offset:8448
	v_mfma_f32_16x16x32_bf16 v[10:13], v[106:109], v[178:181], v[10:13]
	ds_read_b64 v[106:107], v220 offset:16640
	ds_read_b64 v[108:109], v221 offset:16640
	v_mfma_f32_16x16x32_bf16 v[14:17], v[110:113], v[178:181], v[14:17]
	ds_read_b64 v[110:111], v220 offset:24832
	ds_read_b64 v[112:113], v221 offset:24832
	v_mfma_f32_16x16x32_bf16 v[18:21], v[114:117], v[178:181], v[18:21]
	ds_read_b64 v[114:115], v220 offset:33024
	ds_read_b64 v[116:117], v221 offset:33024
	v_mfma_f32_16x16x32_bf16 v[22:25], v[118:121], v[178:181], v[22:25]
	ds_read_b64 v[118:119], v220 offset:41216
	ds_read_b64 v[120:121], v221 offset:41216
	v_mfma_f32_16x16x32_bf16 v[26:29], v[122:125], v[178:181], v[26:29]
	ds_read_b64 v[122:123], v220 offset:49408
	ds_read_b64 v[124:125], v221 offset:49408
	v_mfma_f32_16x16x32_bf16 v[30:33], v[126:129], v[178:181], v[30:33]
	ds_read_b64 v[126:127], v220 offset:57600
	ds_read_b64 v[128:129], v221 offset:57600
	s_waitcnt lgkmcnt(15)
	v_mfma_f32_16x16x32_bf16 v[2:5], v[130:133], v[182:185], v[2:5]
	ds_read_b64 v[130:131], v222 offset:256
	ds_read_b64 v[132:133], v223 offset:256
	v_mfma_f32_16x16x32_bf16 v[6:9], v[134:137], v[182:185], v[6:9]
	ds_read_b64 v[134:135], v222 offset:8448
	ds_read_b64 v[136:137], v223 offset:8448
	v_mfma_f32_16x16x32_bf16 v[10:13], v[138:141], v[182:185], v[10:13]
	ds_read_b64 v[138:139], v222 offset:16640
	ds_read_b64 v[140:141], v223 offset:16640
	v_mfma_f32_16x16x32_bf16 v[14:17], v[142:145], v[182:185], v[14:17]
	ds_read_b64 v[142:143], v222 offset:24832
	ds_read_b64 v[144:145], v223 offset:24832
	v_mfma_f32_16x16x32_bf16 v[18:21], v[146:149], v[182:185], v[18:21]
	ds_read_b64 v[146:147], v222 offset:33024
	ds_read_b64 v[148:149], v223 offset:33024
	v_mfma_f32_16x16x32_bf16 v[22:25], v[150:153], v[182:185], v[22:25]
	ds_read_b64 v[150:151], v222 offset:41216
	ds_read_b64 v[152:153], v223 offset:41216
	v_mfma_f32_16x16x32_bf16 v[26:29], v[154:157], v[182:185], v[26:29]
	ds_read_b64 v[154:155], v222 offset:49408
	ds_read_b64 v[156:157], v223 offset:49408
	v_mfma_f32_16x16x32_bf16 v[30:33], v[158:161], v[182:185], v[30:33]
	ds_read_b64 v[158:159], v222 offset:57600
	ds_read_b64 v[160:161], v223 offset:57600
	s_waitcnt lgkmcnt(15)
; #define LAS __attribute__((address_space(3)))
; #define MFMA16(a, b, c) __builtin_amdgcn_mfma_f32_16x16x32_bf16((a), (b), (c), 0, 0, 0)
; DI void xattn_phase(LAS unsigned char* L, const bf16* Qx, const bf16* memK, const bf16* memVT, bf16* Ox, int G, int bid, int tid, unsigned long long& tsec) {
;     ...
;     for (int unit = bid; unit < 512; unit += G) {
;         const int j = unit & 31, h = (unit >> 5) & 3, b = unit >> 7;
;         const int nun = unit + G < 512 ? unit + G : unit, hn = (nun >> 5) & 3, bn = nun >> 7;
;         asm volatile("" : "+v"(ra[0]), "+v"(ra[1]), "+v"(ra[2]), "+v"(ra[3]), "+v"(ra[4]), "+v"(ra[5]), "+v"(ra[6]), "+v"(ra[7]));
;         asm volatile("" : "+v"(rb[0]), "+v"(rb[1]), "+v"(rb[2]), "+v"(rb[3]), "+v"(rb[4]), "+v"(rb[5]), "+v"(rb[6]), "+v"(rb[7]));
;         const int tok0 = b * T + 128 * j; const size_t tq = (size_t)(tok0 + 16 * wid + fr);
;     ...
;             for (int pp = 0; pp < 8; ++pp)
; #pragma unroll
;                 for (int d4 = 0; d4 < 2; ++d4) { bf16x8 vf[4];
; #pragma unroll
;                     for (int dq = 0; dq < 4; ++dq) { const int dt = 4 * d4 + dq; const LAS unsigned char* vb_ = ((dt & 1) ? vod : vev) + 16 * dt * VSTR + 64 * pp;
;                         const s16x4 lo = *(const LAS s16x4*)(vb_ + (((2 * dt) & 4) << 3)), hi = *(const LAS s16x4*)(vb_ + ((((2 * dt) & 4) ^ 4) << 3)); vf[dq] = __builtin_shufflevector(lo, hi, 0, 1, 2, 3, 4, 5, 6, 7); }
; #pragma unroll
;                     for (int dq = 0; dq < 4; ++dq) o[4 * d4 + dq] = MFMA16(vf[dq], pf[pp], o[4 * d4 + dq]);
;                 }
	v_mfma_f32_16x16x32_bf16 v[2:5], v[98:101], v[186:189], v[2:5]
	v_mfma_f32_16x16x32_bf16 v[6:9], v[102:105], v[186:189], v[6:9]
	v_mfma_f32_16x16x32_bf16 v[10:13], v[106:109], v[186:189], v[10:13]
	v_mfma_f32_16x16x32_bf16 v[14:17], v[110:113], v[186:189], v[14:17]
	v_mfma_f32_16x16x32_bf16 v[18:21], v[114:117], v[186:189], v[18:21]
	v_mfma_f32_16x16x32_bf16 v[22:25], v[118:121], v[186:189], v[22:25]
	v_mfma_f32_16x16x32_bf16 v[26:29], v[122:125], v[186:189], v[26:29]
	v_mfma_f32_16x16x32_bf16 v[30:33], v[126:129], v[186:189], v[30:33]
	s_waitcnt lgkmcnt(0)
	v_mfma_f32_16x16x32_bf16 v[2:5], v[130:133], v[190:193], v[2:5]
	v_mfma_f32_16x16x32_bf16 v[6:9], v[134:137], v[190:193], v[6:9]
	v_mfma_f32_16x16x32_bf16 v[10:13], v[138:141], v[190:193], v[10:13]
	v_mfma_f32_16x16x32_bf16 v[14:17], v[142:145], v[190:193], v[14:17]
	v_mfma_f32_16x16x32_bf16 v[18:21], v[146:149], v[190:193], v[18:21]
	v_mfma_f32_16x16x32_bf16 v[22:25], v[150:153], v[190:193], v[22:25]
	v_mfma_f32_16x16x32_bf16 v[26:29], v[154:157], v[190:193], v[26:29]
	v_mfma_f32_16x16x32_bf16 v[30:33], v[158:161], v[190:193], v[30:33]
	s_waitcnt vmcnt(0)
	s_barrier
	s_add_u32 s18, s17, 32
	s_bitcmp1_b32 s18, 5
	s_cbranch_scc0 .Lxa_last
	s_and_b32 s44, s18, 31
	s_bfe_u32 s45, s18, 0x20005
	s_lshr_b32 s46, s18, 7
	s_lshl_b32 s47, s46, 12
	s_lshl_b32 s44, s44, 7
	s_add_u32 s47, s47, s44
	s_lshl_b32 s47, s47, 11
	s_lshl_b32 s44, s45, 9
	s_add_u32 s47, s47, s44
	s_add_u32 s20, s0, s47
	s_addc_u32 s21, s1, 0
	s_lshl_b32 s47, s46, 19
	s_add_u32 s47, s47, s44
	s_add_u32 s24, s36, s47
	s_addc_u32 s25, s37, 0
	s_lshl_b32 s47, s45, 19
	s_lshl_b32 s44, s46, 9
	s_add_u32 s47, s47, s44
	s_add_u32 s42, s2, s47
	s_addc_u32 s43, s3, 0
	s_add_u32 s44, s24, 0
	s_addc_u32 s45, s25, 0
	s_add_u32 s46, s44, 0x8000
	s_addc_u32 s47, s45, 0
	s_add_u32 m0, s49, 0
	s_nop 0
	global_load_lds_dwordx4 v198, s[44:45]
	s_add_u32 m0, s49, 1024
	s_nop 0
	global_load_lds_dwordx4 v199, s[44:45]
	s_add_u32 m0, s49, 2048
	s_nop 0
	global_load_lds_dwordx4 v200, s[44:45]
	s_add_u32 m0, s49, 3072
	s_nop 0
	global_load_lds_dwordx4 v201, s[44:45]
	s_add_u32 m0, s49, 4096
	s_nop 0
	global_load_lds_dwordx4 v198, s[46:47]
	s_add_u32 m0, s49, 5120
	s_nop 0
	global_load_lds_dwordx4 v199, s[46:47]
	s_add_u32 m0, s49, 6144
	s_nop 0
	global_load_lds_dwordx4 v200, s[46:47]
	s_add_u32 m0, s49, 7168
	s_nop 0
	global_load_lds_dwordx4 v201, s[46:47]
	global_load_dwordx4 v[66:69], v232, s[20:21]
	global_load_dwordx4 v[70:73], v232, s[20:21] offset:64
	global_load_dwordx4 v[74:77], v232, s[20:21] offset:128
	global_load_dwordx4 v[78:81], v232, s[20:21] offset:192
	global_load_dwordx4 v[82:85], v232, s[20:21] offset:256
	global_load_dwordx4 v[86:89], v232, s[20:21] offset:320
	global_load_dwordx4 v[90:93], v232, s[20:21] offset:384
	global_load_dwordx4 v[94:97], v232, s[20:21] offset:448
	ds_read_b64 v[98:99], v224 offset:0
	ds_read_b64 v[100:101], v225 offset:0
	ds_read_b64 v[102:103], v224 offset:8192
	ds_read_b64 v[104:105], v225 offset:8192
	ds_read_b64 v[106:107], v224 offset:16384
	ds_read_b64 v[108:109], v225 offset:16384
	ds_read_b64 v[110:111], v224 offset:24576
	ds_read_b64 v[112:113], v225 offset:24576
	ds_read_b64 v[114:115], v224 offset:32768
	ds_read_b64 v[116:117], v225 offset:32768
	ds_read_b64 v[118:119], v224 offset:40960
	ds_read_b64 v[120:121], v225 offset:40960
	ds_read_b64 v[122:123], v224 offset:49152
	ds_read_b64 v[124:125], v225 offset:49152
	ds_read_b64 v[126:127], v224 offset:57344
	ds_read_b64 v[128:129], v225 offset:57344
	ds_read_b64 v[130:131], v226 offset:0
	ds_read_b64 v[132:133], v227 offset:0
	ds_read_b64 v[134:135], v226 offset:8192
	ds_read_b64 v[136:137], v227 offset:8192
	ds_read_b64 v[138:139], v226 offset:16384
	ds_read_b64 v[140:141], v227 offset:16384
	ds_read_b64 v[142:143], v226 offset:24576
	ds_read_b64 v[144:145], v227 offset:24576
	ds_read_b64 v[146:147], v226 offset:32768
	ds_read_b64 v[148:149], v227 offset:32768
	ds_read_b64 v[150:151], v226 offset:40960
	ds_read_b64 v[152:153], v227 offset:40960
	ds_read_b64 v[154:155], v226 offset:49152
	ds_read_b64 v[156:157], v227 offset:49152
	ds_read_b64 v[158:159], v226 offset:57344
	ds_read_b64 v[160:161], v227 offset:57344
	s_waitcnt lgkmcnt(15)
	v_mfma_f32_16x16x32_bf16 v[34:37], v[98:101], v[162:165], 0
	ds_read_b64 v[98:99], v228 offset:0
	ds_read_b64 v[100:101], v229 offset:0
	v_mfma_f32_16x16x32_bf16 v[38:41], v[102:105], v[162:165], 0
	ds_read_b64 v[102:103], v228 offset:8192
	ds_read_b64 v[104:105], v229 offset:8192
	v_mfma_f32_16x16x32_bf16 v[42:45], v[106:109], v[162:165], 0
	ds_read_b64 v[106:107], v228 offset:16384
	ds_read_b64 v[108:109], v229 offset:16384
	v_mfma_f32_16x16x32_bf16 v[46:49], v[110:113], v[162:165], 0
	ds_read_b64 v[110:111], v228 offset:24576
	ds_read_b64 v[112:113], v229 offset:24576
	v_mfma_f32_16x16x32_bf16 v[50:53], v[114:117], v[162:165], 0
	ds_read_b64 v[114:115], v228 offset:32768
	ds_read_b64 v[116:117], v229 offset:32768
	v_mfma_f32_16x16x32_bf16 v[54:57], v[118:121], v[162:165], 0
	ds_read_b64 v[118:119], v228 offset:40960
	ds_read_b64 v[120:121], v229 offset:40960
	v_mfma_f32_16x16x32_bf16 v[58:61], v[122:125], v[162:165], 0
	ds_read_b64 v[122:123], v228 offset:49152
	ds_read_b64 v[124:125], v229 offset:49152
	v_mfma_f32_16x16x32_bf16 v[62:65], v[126:129], v[162:165], 0
	ds_read_b64 v[126:127], v228 offset:57344
	ds_read_b64 v[128:129], v229 offset:57344
	s_waitcnt lgkmcnt(15)
; #define LAS __attribute__((address_space(3)))
; #define MFMA16(a, b, c) __builtin_amdgcn_mfma_f32_16x16x32_bf16((a), (b), (c), 0, 0, 0)
; DI void xattn_phase(LAS unsigned char* L, const bf16* Qx, const bf16* memK, const bf16* memVT, bf16* Ox, int G, int bid, int tid, unsigned long long& tsec) {
;     ...
;             for (int pp = 0; pp < 8; ++pp)
; #pragma unroll
;                 for (int d4 = 0; d4 < 2; ++d4) { bf16x8 vf[4];
; #pragma unroll
;                     for (int dq = 0; dq < 4; ++dq) { const int dt = 4 * d4 + dq; const LAS unsigned char* vb_ = ((dt & 1) ? vod : vev) + 16 * dt * VSTR + 64 * pp;
;                         const s16x4 lo = *(const LAS s16x4*)(vb_ + (((2 * dt) & 4) << 3)), hi = *(const LAS s16x4*)(vb_ + ((((2 * dt) & 4) ^ 4) << 3)); vf[dq] = __builtin_shufflevector(lo, hi, 0, 1, 2, 3, 4, 5, 6, 7); }
; #pragma unroll
;                     for (int dq = 0; dq < 4; ++dq) o[4 * d4 + dq] = MFMA16(vf[dq], pf[pp], o[4 * d4 + dq]);
;                 }
	v_mfma_f32_16x16x32_bf16 v[34:37], v[130:133], v[166:169], v[34:37]
	ds_read_b64 v[130:131], v230 offset:0
	ds_read_b64 v[132:133], v231 offset:0
	v_mfma_f32_16x16x32_bf16 v[38:41], v[134:137], v[166:169], v[38:41]
	ds_read_b64 v[134:135], v230 offset:8192
	ds_read_b64 v[136:137], v231 offset:8192
	v_mfma_f32_16x16x32_bf16 v[42:45], v[138:141], v[166:169], v[42:45]
	ds_read_b64 v[138:139], v230 offset:16384
	ds_read_b64 v[140:141], v231 offset:16384
	v_mfma_f32_16x16x32_bf16 v[46:49], v[142:145], v[166:169], v[46:49]
	ds_read_b64 v[142:143], v230 offset:24576
	ds_read_b64 v[144:145], v231 offset:24576
	v_mfma_f32_16x16x32_bf16 v[50:53], v[146:149], v[166:169], v[50:53]
	ds_read_b64 v[146:147], v230 offset:32768
	ds_read_b64 v[148:149], v231 offset:32768
	v_mfma_f32_16x16x32_bf16 v[54:57], v[150:153], v[166:169], v[54:57]
	ds_read_b64 v[150:151], v230 offset:40960
	ds_read_b64 v[152:153], v231 offset:40960
	v_mfma_f32_16x16x32_bf16 v[58:61], v[154:157], v[166:169], v[58:61]
	ds_read_b64 v[154:155], v230 offset:49152
	ds_read_b64 v[156:157], v231 offset:49152
	v_mfma_f32_16x16x32_bf16 v[62:65], v[158:161], v[166:169], v[62:65]
	ds_read_b64 v[158:159], v230 offset:57344
	ds_read_b64 v[160:161], v231 offset:57344
	s_waitcnt lgkmcnt(15)
	v_mfma_f32_16x16x32_bf16 v[34:37], v[98:101], v[170:173], v[34:37]
	ds_read_b64 v[98:99], v224 offset:256
	ds_read_b64 v[100:101], v225 offset:256
	v_mfma_f32_16x16x32_bf16 v[38:41], v[102:105], v[170:173], v[38:41]
	ds_read_b64 v[102:103], v224 offset:8448
	ds_read_b64 v[104:105], v225 offset:8448
	v_mfma_f32_16x16x32_bf16 v[42:45], v[106:109], v[170:173], v[42:45]
	ds_read_b64 v[106:107], v224 offset:16640
	ds_read_b64 v[108:109], v225 offset:16640
	v_mfma_f32_16x16x32_bf16 v[46:49], v[110:113], v[170:173], v[46:49]
	ds_read_b64 v[110:111], v224 offset:24832
	ds_read_b64 v[112:113], v225 offset:24832
	v_mfma_f32_16x16x32_bf16 v[50:53], v[114:117], v[170:173], v[50:53]
	ds_read_b64 v[114:115], v224 offset:33024
	ds_read_b64 v[116:117], v225 offset:33024
	v_mfma_f32_16x16x32_bf16 v[54:57], v[118:121], v[170:173], v[54:57]
	ds_read_b64 v[118:119], v224 offset:41216
	ds_read_b64 v[120:121], v225 offset:41216
	v_mfma_f32_16x16x32_bf16 v[58:61], v[122:125], v[170:173], v[58:61]
	ds_read_b64 v[122:123], v224 offset:49408
	ds_read_b64 v[124:125], v225 offset:49408
	v_mfma_f32_16x16x32_bf16 v[62:65], v[126:129], v[170:173], v[62:65]
	ds_read_b64 v[126:127], v224 offset:57600
	ds_read_b64 v[128:129], v225 offset:57600
	s_waitcnt lgkmcnt(15)
	v_mfma_f32_16x16x32_bf16 v[34:37], v[130:133], v[174:177], v[34:37]
	ds_read_b64 v[130:131], v226 offset:256
	ds_read_b64 v[132:133], v227 offset:256
	v_mfma_f32_16x16x32_bf16 v[38:41], v[134:137], v[174:177], v[38:41]
	ds_read_b64 v[134:135], v226 offset:8448
	ds_read_b64 v[136:137], v227 offset:8448
	v_mfma_f32_16x16x32_bf16 v[42:45], v[138:141], v[174:177], v[42:45]
	ds_read_b64 v[138:139], v226 offset:16640
	ds_read_b64 v[140:141], v227 offset:16640
	v_mfma_f32_16x16x32_bf16 v[46:49], v[142:145], v[174:177], v[46:49]
	ds_read_b64 v[142:143], v226 offset:24832
	ds_read_b64 v[144:145], v227 offset:24832
	v_mfma_f32_16x16x32_bf16 v[50:53], v[146:149], v[174:177], v[50:53]
	ds_read_b64 v[146:147], v226 offset:33024
	ds_read_b64 v[148:149], v227 offset:33024
	v_mfma_f32_16x16x32_bf16 v[54:57], v[150:153], v[174:177], v[54:57]
	ds_read_b64 v[150:151], v226 offset:41216
	ds_read_b64 v[152:153], v227 offset:41216
	v_mfma_f32_16x16x32_bf16 v[58:61], v[154:157], v[174:177], v[58:61]
	ds_read_b64 v[154:155], v226 offset:49408
	ds_read_b64 v[156:157], v227 offset:49408
	v_mfma_f32_16x16x32_bf16 v[62:65], v[158:161], v[174:177], v[62:65]
	ds_read_b64 v[158:159], v226 offset:57600
	ds_read_b64 v[160:161], v227 offset:57600
	s_waitcnt lgkmcnt(15)
	v_mfma_f32_16x16x32_bf16 v[34:37], v[98:101], v[178:181], v[34:37]
	ds_read_b64 v[98:99], v228 offset:256
	ds_read_b64 v[100:101], v229 offset:256
	v_mfma_f32_16x16x32_bf16 v[38:41], v[102:105], v[178:181], v[38:41]
	ds_read_b64 v[102:103], v228 offset:8448
	ds_read_b64 v[104:105], v229 offset:8448
	v_mfma_f32_16x16x32_bf16 v[42:45], v[106:109], v[178:181], v[42:45]
	ds_read_b64 v[106:107], v228 offset:16640
	ds_read_b64 v[108:109], v229 offset:16640
	v_mfma_f32_16x16x32_bf16 v[46:49], v[110:113], v[178:181], v[46:49]
	ds_read_b64 v[110:111], v228 offset:24832
	ds_read_b64 v[112:113], v229 offset:24832
	v_mfma_f32_16x16x32_bf16 v[50:53], v[114:117], v[178:181], v[50:53]
	ds_read_b64 v[114:115], v228 offset:33024
	ds_read_b64 v[116:117], v229 offset:33024
	v_mfma_f32_16x16x32_bf16 v[54:57], v[118:121], v[178:181], v[54:57]
	ds_read_b64 v[118:119], v228 offset:41216
	ds_read_b64 v[120:121], v229 offset:41216
	v_mfma_f32_16x16x32_bf16 v[58:61], v[122:125], v[178:181], v[58:61]
	ds_read_b64 v[122:123], v228 offset:49408
	ds_read_b64 v[124:125], v229 offset:49408
	v_mfma_f32_16x16x32_bf16 v[62:65], v[126:129], v[178:181], v[62:65]
	ds_read_b64 v[126:127], v228 offset:57600
	ds_read_b64 v[128:129], v229 offset:57600
	s_waitcnt lgkmcnt(15)
; #define LAS __attribute__((address_space(3)))
; DI unsigned pk2(float lo, float hi) { const bf2_t r = __builtin_convertvector((f32x2_t){lo, hi}, bf2_t); return __builtin_bit_cast(unsigned, r); }
; #define MFMA16(a, b, c) __builtin_amdgcn_mfma_f32_16x16x32_bf16((a), (b), (c), 0, 0, 0)
; #define DSEC(k) do { if (PROBE_DSEC) { const unsigned long long tn_ = __builtin_amdgcn_s_memrealtime(); if (PROBE_DSEC == (k)) tsec += tn_ - tl_; tl_ = tn_; } } while (0)
; DI void xattn_phase(LAS unsigned char* L, const bf16* Qx, const bf16* memK, const bf16* memVT, bf16* Ox, int G, int bid, int tid, unsigned long long& tsec) {
;     ...
;             for (int pp = 0; pp < 8; ++pp)
; #pragma unroll
;                 for (int d4 = 0; d4 < 2; ++d4) { bf16x8 vf[4];
; #pragma unroll
;                     for (int dq = 0; dq < 4; ++dq) { const int dt = 4 * d4 + dq; const LAS unsigned char* vb_ = ((dt & 1) ? vod : vev) + 16 * dt * VSTR + 64 * pp;
;                         const s16x4 lo = *(const LAS s16x4*)(vb_ + (((2 * dt) & 4) << 3)), hi = *(const LAS s16x4*)(vb_ + ((((2 * dt) & 4) ^ 4) << 3)); vf[dq] = __builtin_shufflevector(lo, hi, 0, 1, 2, 3, 4, 5, 6, 7); }
; #pragma unroll
;                     for (int dq = 0; dq < 4; ++dq) o[4 * d4 + dq] = MFMA16(vf[dq], pf[pp], o[4 * d4 + dq]);
;                 }
;             { bf16* op = Ox + tq * D + h * 256 + 128 * hh + 4 * fq;
; #pragma unroll
;               for (int dt = 0; dt < 8; ++dt) *(unsigned long long*)(op + 16 * dt) = (unsigned long long)pk2(o[dt][0] * inv, o[dt][1] * inv) | ((unsigned long long)pk2(o[dt][2] * inv, o[dt][3] * inv) << 32); }
;         }
;         DSEC(14);
	v_mfma_f32_16x16x32_bf16 v[34:37], v[130:133], v[182:185], v[34:37]
	ds_read_b64 v[130:131], v230 offset:256
	ds_read_b64 v[132:133], v231 offset:256
	v_mfma_f32_16x16x32_bf16 v[38:41], v[134:137], v[182:185], v[38:41]
	ds_read_b64 v[134:135], v230 offset:8448
	ds_read_b64 v[136:137], v231 offset:8448
	v_mfma_f32_16x16x32_bf16 v[42:45], v[138:141], v[182:185], v[42:45]
	ds_read_b64 v[138:139], v230 offset:16640
	ds_read_b64 v[140:141], v231 offset:16640
	v_mfma_f32_16x16x32_bf16 v[46:49], v[142:145], v[182:185], v[46:49]
	ds_read_b64 v[142:143], v230 offset:24832
	ds_read_b64 v[144:145], v231 offset:24832
	v_mfma_f32_16x16x32_bf16 v[50:53], v[146:149], v[182:185], v[50:53]
	ds_read_b64 v[146:147], v230 offset:33024
	ds_read_b64 v[148:149], v231 offset:33024
	v_mfma_f32_16x16x32_bf16 v[54:57], v[150:153], v[182:185], v[54:57]
	ds_read_b64 v[150:151], v230 offset:41216
	ds_read_b64 v[152:153], v231 offset:41216
	v_mfma_f32_16x16x32_bf16 v[58:61], v[154:157], v[182:185], v[58:61]
	ds_read_b64 v[154:155], v230 offset:49408
	ds_read_b64 v[156:157], v231 offset:49408
	v_mfma_f32_16x16x32_bf16 v[62:65], v[158:161], v[182:185], v[62:65]
	ds_read_b64 v[158:159], v230 offset:57600
	ds_read_b64 v[160:161], v231 offset:57600
	s_waitcnt lgkmcnt(15)
	v_mfma_f32_16x16x32_bf16 v[34:37], v[98:101], v[186:189], v[34:37]
	v_mfma_f32_16x16x32_bf16 v[38:41], v[102:105], v[186:189], v[38:41]
	v_mfma_f32_16x16x32_bf16 v[42:45], v[106:109], v[186:189], v[42:45]
	v_mfma_f32_16x16x32_bf16 v[46:49], v[110:113], v[186:189], v[46:49]
	v_mfma_f32_16x16x32_bf16 v[50:53], v[114:117], v[186:189], v[50:53]
	v_mfma_f32_16x16x32_bf16 v[54:57], v[118:121], v[186:189], v[54:57]
	v_mfma_f32_16x16x32_bf16 v[58:61], v[122:125], v[186:189], v[58:61]
	v_mfma_f32_16x16x32_bf16 v[62:65], v[126:129], v[186:189], v[62:65]
	s_waitcnt lgkmcnt(0)
	v_mfma_f32_16x16x32_bf16 v[34:37], v[130:133], v[190:193], v[34:37]
	v_mfma_f32_16x16x32_bf16 v[38:41], v[134:137], v[190:193], v[38:41]
	v_mfma_f32_16x16x32_bf16 v[42:45], v[138:141], v[190:193], v[42:45]
	v_mfma_f32_16x16x32_bf16 v[46:49], v[142:145], v[190:193], v[46:49]
	v_mfma_f32_16x16x32_bf16 v[50:53], v[146:149], v[190:193], v[50:53]
	v_mfma_f32_16x16x32_bf16 v[54:57], v[150:153], v[190:193], v[54:57]
	v_mfma_f32_16x16x32_bf16 v[58:61], v[154:157], v[190:193], v[58:61]
	v_mfma_f32_16x16x32_bf16 v[62:65], v[158:161], v[190:193], v[62:65]
	v_mul_f32_e32 v2, v0, v2
	v_mul_f32_e32 v3, v0, v3
	v_mul_f32_e32 v4, v0, v4
	v_mul_f32_e32 v5, v0, v5
	v_cvt_pk_bf16_f32 v2, v2, v3
	v_cvt_pk_bf16_f32 v3, v4, v5
	global_store_dwordx2 v233, v[2:3], s[22:23]
	v_mul_f32_e32 v6, v0, v6
	v_mul_f32_e32 v7, v0, v7
	v_mul_f32_e32 v8, v0, v8
	v_mul_f32_e32 v9, v0, v9
	v_cvt_pk_bf16_f32 v6, v6, v7
	v_cvt_pk_bf16_f32 v7, v8, v9
	global_store_dwordx2 v233, v[6:7], s[22:23] offset:32
	v_mul_f32_e32 v10, v0, v10
	v_mul_f32_e32 v11, v0, v11
	v_mul_f32_e32 v12, v0, v12
	v_mul_f32_e32 v13, v0, v13
	v_cvt_pk_bf16_f32 v10, v10, v11
	v_cvt_pk_bf16_f32 v11, v12, v13
	global_store_dwordx2 v233, v[10:11], s[22:23] offset:64
	v_mul_f32_e32 v14, v0, v14
	v_mul_f32_e32 v15, v0, v15
	v_mul_f32_e32 v16, v0, v16
	v_mul_f32_e32 v17, v0, v17
	v_cvt_pk_bf16_f32 v14, v14, v15
	v_cvt_pk_bf16_f32 v15, v16, v17
	global_store_dwordx2 v233, v[14:15], s[22:23] offset:96
	v_mul_f32_e32 v18, v0, v18
	v_mul_f32_e32 v19, v0, v19
	v_mul_f32_e32 v20, v0, v20
	v_mul_f32_e32 v21, v0, v21
	v_cvt_pk_bf16_f32 v18, v18, v19
	v_cvt_pk_bf16_f32 v19, v20, v21
	global_store_dwordx2 v233, v[18:19], s[22:23] offset:128
	v_mul_f32_e32 v22, v0, v22
	v_mul_f32_e32 v23, v0, v23
	v_mul_f32_e32 v24, v0, v24
	v_mul_f32_e32 v25, v0, v25
	v_cvt_pk_bf16_f32 v22, v22, v23
	v_cvt_pk_bf16_f32 v23, v24, v25
	global_store_dwordx2 v233, v[22:23], s[22:23] offset:160
	v_mul_f32_e32 v26, v0, v26
	v_mul_f32_e32 v27, v0, v27
	v_mul_f32_e32 v28, v0, v28
	v_mul_f32_e32 v29, v0, v29
	v_cvt_pk_bf16_f32 v26, v26, v27
	v_cvt_pk_bf16_f32 v27, v28, v29
	global_store_dwordx2 v233, v[26:27], s[22:23] offset:192
	v_mul_f32_e32 v30, v0, v30
	v_mul_f32_e32 v31, v0, v31
	v_mul_f32_e32 v32, v0, v32
	v_mul_f32_e32 v33, v0, v33
	v_cvt_pk_bf16_f32 v30, v30, v31
	v_cvt_pk_bf16_f32 v31, v32, v33
	global_store_dwordx2 v233, v[30:31], s[22:23] offset:224
	v_mul_f32_e32 v34, v0, v34
	v_mul_f32_e32 v35, v0, v35
	v_mul_f32_e32 v36, v0, v36
	v_mul_f32_e32 v37, v0, v37
	v_cvt_pk_bf16_f32 v34, v34, v35
	v_cvt_pk_bf16_f32 v35, v36, v37
	global_store_dwordx2 v233, v[34:35], s[22:23] offset:256
	v_mul_f32_e32 v38, v0, v38
	v_mul_f32_e32 v39, v0, v39
	v_mul_f32_e32 v40, v0, v40
	v_mul_f32_e32 v41, v0, v41
	v_cvt_pk_bf16_f32 v38, v38, v39
	v_cvt_pk_bf16_f32 v39, v40, v41
	global_store_dwordx2 v233, v[38:39], s[22:23] offset:288
	v_mul_f32_e32 v42, v0, v42
	v_mul_f32_e32 v43, v0, v43
	v_mul_f32_e32 v44, v0, v44
	v_mul_f32_e32 v45, v0, v45
	v_cvt_pk_bf16_f32 v42, v42, v43
	v_cvt_pk_bf16_f32 v43, v44, v45
	global_store_dwordx2 v233, v[42:43], s[22:23] offset:320
	v_mul_f32_e32 v46, v0, v46
	v_mul_f32_e32 v47, v0, v47
	v_mul_f32_e32 v48, v0, v48
	v_mul_f32_e32 v49, v0, v49
	v_cvt_pk_bf16_f32 v46, v46, v47
	v_cvt_pk_bf16_f32 v47, v48, v49
	global_store_dwordx2 v233, v[46:47], s[22:23] offset:352
	v_mul_f32_e32 v50, v0, v50
	v_mul_f32_e32 v51, v0, v51
	v_mul_f32_e32 v52, v0, v52
	v_mul_f32_e32 v53, v0, v53
	v_cvt_pk_bf16_f32 v50, v50, v51
	v_cvt_pk_bf16_f32 v51, v52, v53
	global_store_dwordx2 v233, v[50:51], s[22:23] offset:384
	v_mul_f32_e32 v54, v0, v54
	v_mul_f32_e32 v55, v0, v55
	v_mul_f32_e32 v56, v0, v56
	v_mul_f32_e32 v57, v0, v57
	v_cvt_pk_bf16_f32 v54, v54, v55
	v_cvt_pk_bf16_f32 v55, v56, v57
	global_store_dwordx2 v233, v[54:55], s[22:23] offset:416
	v_mul_f32_e32 v58, v0, v58
	v_mul_f32_e32 v59, v0, v59
	v_mul_f32_e32 v60, v0, v60
	v_mul_f32_e32 v61, v0, v61
	v_cvt_pk_bf16_f32 v58, v58, v59
	v_cvt_pk_bf16_f32 v59, v60, v61
	global_store_dwordx2 v233, v[58:59], s[22:23] offset:448
	v_mul_f32_e32 v62, v0, v62
	v_mul_f32_e32 v63, v0, v63
	v_mul_f32_e32 v64, v0, v64
	v_mul_f32_e32 v65, v0, v65
	v_cvt_pk_bf16_f32 v62, v62, v63
	v_cvt_pk_bf16_f32 v63, v64, v65
	global_store_dwordx2 v233, v[62:63], s[22:23] offset:480
	s_mov_b32 s17, s18
	s_and_b32 s44, s17, 31
	s_bfe_u32 s45, s17, 0x20005
	s_lshr_b32 s46, s17, 7
	s_lshl_b32 s47, s46, 12
	s_lshl_b32 s44, s44, 7
	s_add_u32 s47, s47, s44
	s_lshl_b32 s47, s47, 11
	s_lshl_b32 s44, s45, 9
	s_add_u32 s47, s47, s44
	s_add_u32 s22, s38, s47
	s_addc_u32 s23, s39, 0
	s_waitcnt vmcnt(16)
	s_barrier
	s_branch .Lxa_loop
